# P5/P6 gate+residual epilogues: batched global loads with counted vmcnt instead of load-wait-load serialization
# speedup vs baseline: 1.0056x; 1.0056x over previous
; __device__ __forceinline__ float bf_lo(unsigned u) { return __uint_as_float(u << 16); }
; __device__ __forceinline__ float bf_hi(unsigned u) { return __uint_as_float(u & 0xffff0000u); }
; __device__ __forceinline__ u32x4 pk8(const f32x4& a, const f32x4& b) { u32x4 w; w.x = pk(a[0], a[1]); w.y = pk(a[2], a[3]); w.z = pk(b[0], b[1]); w.w = pk(b[2], b[3]); return w; }
;     __device__ __forceinline__ void operator()(const f32x4 (&acc)[2][2][4][2], const pg8::Unit& u, int wr, int wc, int fr, int fq) const { if (u.job) kv(acc, u, wr, wc, fr, fq); else q(acc, u, wr, wc, fr, fq); }
;     __device__ __forceinline__ void operator()(const f32x4 (&acc)[2][2][4][2], const pg8::Unit& u, int wr, int wc, int fr, int fq) const { if (u.job) e1(acc, u, wr, wc, fr, fq); else e0(acc, u, wr, wc, fr, fq); }
;     __device__ __forceinline__ void operator()(const f32x4 (&acc)[2][2][4][2], const pg8::Unit& u, int wr, int wc, int fr, int fq) const {
;         const int row0 = u.pm * 256 + wr * 64 + fr; const int col0 = u.pn * 256 + wc * 32 + 8 * fq;
; #pragma unroll
;         for (int ai = 0; ai < 2; ++ai)
; #pragma unroll
;             for (int m = 0; m < 4; ++m)
; #pragma unroll
;                 for (int bj = 0; bj < 2; ++bj) {
;                     const size_t off = (size_t)(row0 + ai * 128 + m * 16) * 2048 + col0 + bj * 128;
;                     const u32x4 g = *(const u32x4*)(G + off);
;                     f32x4 v0 = acc[ai][bj][m][0], v1 = acc[ai][bj][m][1];
;                     v0[0] *= bf_lo(g.x); v0[1] *= bf_hi(g.x); v0[2] *= bf_lo(g.y); v0[3] *= bf_hi(g.y);
;                     v1[0] *= bf_lo(g.z); v1[1] *= bf_hi(g.z); v1[2] *= bf_lo(g.w); v1[3] *= bf_hi(g.w);
;                     if (!first) { const u32x4 p = *(const u32x4*)(Mg + off);
;                         v0[0] += bf_lo(p.x); v0[1] += bf_hi(p.x); v0[2] += bf_lo(p.y); v0[3] += bf_hi(p.y);
;                         v1[0] += bf_lo(p.z); v1[1] += bf_hi(p.z); v1[2] += bf_lo(p.w); v1[3] += bf_hi(p.w); }
;                     *(u32x4*)(Mg + off) = pk8(v0, v1);
;                 }
.LBB0_1151:
	v_lshl_add_u32 v193, s3, 8, v158
	v_lshl_or_b32 v140, s30, 8, v160
	v_lshlrev_b32_e32 v140, 1, v140
	v_lshl_add_u32 v140, v193, 12, v140
	v_add_u32_e32 v141, 0x10000, v140
	v_add_u32_e32 v142, 0x20000, v140
	v_add_u32_e32 v143, 0x30000, v140
	v_add_u32_e32 v144, 0x80000, v140
	v_add_u32_e32 v145, 0x90000, v140
	v_add_u32_e32 v182, 0xa0000, v140
	v_add_u32_e32 v183, 0xb0000, v140
	s_nop 15
	s_nop 3
	s_cmp_eq_u32 s2, 0
	v_readlane_b32 s38, v255, 20
	v_readlane_b32 s39, v255, 21
	s_cbranch_scc1 .LBB0_1157
	v_readlane_b32 s2, v254, 4
	v_readlane_b32 s3, v254, 5
	s_nop 4
	global_load_dwordx4 v[150:153], v140, s[84:85]
	global_load_dwordx4 v[146:149], v140, s[2:3]
	global_load_dwordx4 v[162:165], v140, s[84:85] offset:256
	global_load_dwordx4 v[154:157], v140, s[2:3] offset:256
	global_load_dwordx4 v[170:173], v141, s[84:85]
	global_load_dwordx4 v[166:169], v141, s[2:3]
	global_load_dwordx4 v[178:181], v141, s[84:85] offset:256
	global_load_dwordx4 v[174:177], v141, s[2:3] offset:256
	global_load_dwordx4 v[206:209], v142, s[84:85]
	global_load_dwordx4 v[202:205], v142, s[2:3]
	global_load_dwordx4 v[214:217], v142, s[84:85] offset:256
	global_load_dwordx4 v[210:213], v142, s[2:3] offset:256
	global_load_dwordx4 v[222:225], v143, s[84:85]
	global_load_dwordx4 v[218:221], v143, s[2:3]
	global_load_dwordx4 v[230:233], v143, s[84:85] offset:256
	global_load_dwordx4 v[226:229], v143, s[2:3] offset:256
	s_waitcnt vmcnt(14)
	v_lshlrev_b32_e32 v234, 16, v146
	v_and_b32_e32 v235, 0xffff0000, v146
	v_lshlrev_b32_e32 v236, 16, v150
	v_and_b32_e32 v237, 0xffff0000, v150
	v_fmac_f32_e32 v236, v124, v234
	v_fmac_f32_e32 v237, v125, v235
	v_cvt_pk_bf16_f32 v146, v236, v237
	v_lshlrev_b32_e32 v244, 16, v147
	v_and_b32_e32 v245, 0xffff0000, v147
	v_lshlrev_b32_e32 v246, 16, v151
	v_and_b32_e32 v247, 0xffff0000, v151
	v_fmac_f32_e32 v246, v126, v244
	v_fmac_f32_e32 v247, v127, v245
	v_cvt_pk_bf16_f32 v147, v246, v247
	v_lshlrev_b32_e32 v248, 16, v148
	v_and_b32_e32 v249, 0xffff0000, v148
	v_lshlrev_b32_e32 v250, 16, v152
	v_and_b32_e32 v251, 0xffff0000, v152
	v_fmac_f32_e32 v250, v120, v248
	v_fmac_f32_e32 v251, v121, v249
	v_cvt_pk_bf16_f32 v148, v250, v251
	v_lshlrev_b32_e32 v188, 16, v149
	v_and_b32_e32 v189, 0xffff0000, v149
	v_lshlrev_b32_e32 v190, 16, v153
	v_and_b32_e32 v191, 0xffff0000, v153
	v_fmac_f32_e32 v190, v122, v188
	v_fmac_f32_e32 v191, v123, v189
	v_cvt_pk_bf16_f32 v149, v190, v191
	global_store_dwordx4 v140, v[146:149], s[84:85]
	global_load_dwordx4 v[150:153], v144, s[84:85]
	global_load_dwordx4 v[146:149], v144, s[2:3]
	s_waitcnt vmcnt(15)
	v_lshlrev_b32_e32 v234, 16, v154
	v_and_b32_e32 v235, 0xffff0000, v154
	v_lshlrev_b32_e32 v236, 16, v162
	v_and_b32_e32 v237, 0xffff0000, v162
	v_fmac_f32_e32 v236, v116, v234
	v_fmac_f32_e32 v237, v117, v235
	v_cvt_pk_bf16_f32 v154, v236, v237
	v_lshlrev_b32_e32 v244, 16, v155
	v_and_b32_e32 v245, 0xffff0000, v155
	v_lshlrev_b32_e32 v246, 16, v163
	v_and_b32_e32 v247, 0xffff0000, v163
	v_fmac_f32_e32 v246, v118, v244
	v_fmac_f32_e32 v247, v119, v245
	v_cvt_pk_bf16_f32 v155, v246, v247
	v_lshlrev_b32_e32 v248, 16, v156
	v_and_b32_e32 v249, 0xffff0000, v156
	v_lshlrev_b32_e32 v250, 16, v164
	v_and_b32_e32 v251, 0xffff0000, v164
	v_fmac_f32_e32 v250, v112, v248
	v_fmac_f32_e32 v251, v113, v249
	v_cvt_pk_bf16_f32 v156, v250, v251
	v_lshlrev_b32_e32 v188, 16, v157
	v_and_b32_e32 v189, 0xffff0000, v157
	v_lshlrev_b32_e32 v190, 16, v165
	v_and_b32_e32 v191, 0xffff0000, v165
	v_fmac_f32_e32 v190, v114, v188
	v_fmac_f32_e32 v191, v115, v189
	v_cvt_pk_bf16_f32 v157, v190, v191
	global_store_dwordx4 v140, v[154:157], s[84:85] offset:256
	global_load_dwordx4 v[162:165], v144, s[84:85] offset:256
	global_load_dwordx4 v[154:157], v144, s[2:3] offset:256
	s_waitcnt vmcnt(16)
	v_lshlrev_b32_e32 v234, 16, v166
	v_and_b32_e32 v235, 0xffff0000, v166
	v_lshlrev_b32_e32 v236, 16, v170
	v_and_b32_e32 v237, 0xffff0000, v170
	v_fmac_f32_e32 v236, v108, v234
	v_fmac_f32_e32 v237, v109, v235
	v_cvt_pk_bf16_f32 v166, v236, v237
	v_lshlrev_b32_e32 v244, 16, v167
	v_and_b32_e32 v245, 0xffff0000, v167
	v_lshlrev_b32_e32 v246, 16, v171
	v_and_b32_e32 v247, 0xffff0000, v171
	v_fmac_f32_e32 v246, v110, v244
	v_fmac_f32_e32 v247, v111, v245
	v_cvt_pk_bf16_f32 v167, v246, v247
	v_lshlrev_b32_e32 v248, 16, v168
	v_and_b32_e32 v249, 0xffff0000, v168
	v_lshlrev_b32_e32 v250, 16, v172
	v_and_b32_e32 v251, 0xffff0000, v172
	v_fmac_f32_e32 v250, v104, v248
	v_fmac_f32_e32 v251, v105, v249
	v_cvt_pk_bf16_f32 v168, v250, v251
	v_lshlrev_b32_e32 v188, 16, v169
	v_and_b32_e32 v189, 0xffff0000, v169
	v_lshlrev_b32_e32 v190, 16, v173
	v_and_b32_e32 v191, 0xffff0000, v173
	v_fmac_f32_e32 v190, v106, v188
	v_fmac_f32_e32 v191, v107, v189
	v_cvt_pk_bf16_f32 v169, v190, v191
	global_store_dwordx4 v141, v[166:169], s[84:85]
	global_load_dwordx4 v[170:173], v145, s[84:85]
	global_load_dwordx4 v[166:169], v145, s[2:3]
	s_waitcnt vmcnt(17)
	v_lshlrev_b32_e32 v234, 16, v174
	v_and_b32_e32 v235, 0xffff0000, v174
	v_lshlrev_b32_e32 v236, 16, v178
	v_and_b32_e32 v237, 0xffff0000, v178
	v_fmac_f32_e32 v236, v100, v234
	v_fmac_f32_e32 v237, v101, v235
	v_cvt_pk_bf16_f32 v174, v236, v237
	v_lshlrev_b32_e32 v244, 16, v175
	v_and_b32_e32 v245, 0xffff0000, v175
	v_lshlrev_b32_e32 v246, 16, v179
	v_and_b32_e32 v247, 0xffff0000, v179
	v_fmac_f32_e32 v246, v102, v244
	v_fmac_f32_e32 v247, v103, v245
	v_cvt_pk_bf16_f32 v175, v246, v247
	v_lshlrev_b32_e32 v248, 16, v176
	v_and_b32_e32 v249, 0xffff0000, v176
	v_lshlrev_b32_e32 v250, 16, v180
	v_and_b32_e32 v251, 0xffff0000, v180
	v_fmac_f32_e32 v250, v96, v248
	v_fmac_f32_e32 v251, v97, v249
	v_cvt_pk_bf16_f32 v176, v250, v251
	v_lshlrev_b32_e32 v188, 16, v177
	v_and_b32_e32 v189, 0xffff0000, v177
	v_lshlrev_b32_e32 v190, 16, v181
	v_and_b32_e32 v191, 0xffff0000, v181
	v_fmac_f32_e32 v190, v98, v188
	v_fmac_f32_e32 v191, v99, v189
	v_cvt_pk_bf16_f32 v177, v190, v191
	global_store_dwordx4 v141, v[174:177], s[84:85] offset:256
	global_load_dwordx4 v[178:181], v145, s[84:85] offset:256
	global_load_dwordx4 v[174:177], v145, s[2:3] offset:256
	s_waitcnt vmcnt(18)
; __device__ __forceinline__ float bf_lo(unsigned u) { return __uint_as_float(u << 16); }
; __device__ __forceinline__ float bf_hi(unsigned u) { return __uint_as_float(u & 0xffff0000u); }
; __device__ __forceinline__ u32x4 pk8(const f32x4& a, const f32x4& b) { u32x4 w; w.x = pk(a[0], a[1]); w.y = pk(a[2], a[3]); w.z = pk(b[0], b[1]); w.w = pk(b[2], b[3]); return w; }
;     __device__ __forceinline__ void operator()(const f32x4 (&acc)[2][2][4][2], const pg8::Unit& u, int wr, int wc, int fr, int fq) const { if (u.job) kv(acc, u, wr, wc, fr, fq); else q(acc, u, wr, wc, fr, fq); }
;     __device__ __forceinline__ void operator()(const f32x4 (&acc)[2][2][4][2], const pg8::Unit& u, int wr, int wc, int fr, int fq) const { if (u.job) e1(acc, u, wr, wc, fr, fq); else e0(acc, u, wr, wc, fr, fq); }
;     __device__ __forceinline__ void operator()(const f32x4 (&acc)[2][2][4][2], const pg8::Unit& u, int wr, int wc, int fr, int fq) const {
;         const int row0 = u.pm * 256 + wr * 64 + fr; const int col0 = u.pn * 256 + wc * 32 + 8 * fq;
; #pragma unroll
;         for (int ai = 0; ai < 2; ++ai)
; #pragma unroll
;             for (int m = 0; m < 4; ++m)
; #pragma unroll
;                 for (int bj = 0; bj < 2; ++bj) {
;                     const size_t off = (size_t)(row0 + ai * 128 + m * 16) * 2048 + col0 + bj * 128;
;                     const u32x4 g = *(const u32x4*)(G + off);
;                     f32x4 v0 = acc[ai][bj][m][0], v1 = acc[ai][bj][m][1];
;                     v0[0] *= bf_lo(g.x); v0[1] *= bf_hi(g.x); v0[2] *= bf_lo(g.y); v0[3] *= bf_hi(g.y);
;                     v1[0] *= bf_lo(g.z); v1[1] *= bf_hi(g.z); v1[2] *= bf_lo(g.w); v1[3] *= bf_hi(g.w);
;                     if (!first) { const u32x4 p = *(const u32x4*)(Mg + off);
;                         v0[0] += bf_lo(p.x); v0[1] += bf_hi(p.x); v0[2] += bf_lo(p.y); v0[3] += bf_hi(p.y);
;                         v1[0] += bf_lo(p.z); v1[1] += bf_hi(p.z); v1[2] += bf_lo(p.w); v1[3] += bf_hi(p.w); }
;                     *(u32x4*)(Mg + off) = pk8(v0, v1);
;                 }
	v_lshlrev_b32_e32 v234, 16, v202
	v_and_b32_e32 v235, 0xffff0000, v202
	v_lshlrev_b32_e32 v236, 16, v206
	v_and_b32_e32 v237, 0xffff0000, v206
	v_fmac_f32_e32 v236, v92, v234
	v_fmac_f32_e32 v237, v93, v235
	v_cvt_pk_bf16_f32 v202, v236, v237
	v_lshlrev_b32_e32 v244, 16, v203
	v_and_b32_e32 v245, 0xffff0000, v203
	v_lshlrev_b32_e32 v246, 16, v207
	v_and_b32_e32 v247, 0xffff0000, v207
	v_fmac_f32_e32 v246, v94, v244
	v_fmac_f32_e32 v247, v95, v245
	v_cvt_pk_bf16_f32 v203, v246, v247
	v_lshlrev_b32_e32 v248, 16, v204
	v_and_b32_e32 v249, 0xffff0000, v204
	v_lshlrev_b32_e32 v250, 16, v208
	v_and_b32_e32 v251, 0xffff0000, v208
	v_fmac_f32_e32 v250, v88, v248
	v_fmac_f32_e32 v251, v89, v249
	v_cvt_pk_bf16_f32 v204, v250, v251
	v_lshlrev_b32_e32 v188, 16, v205
	v_and_b32_e32 v189, 0xffff0000, v205
	v_lshlrev_b32_e32 v190, 16, v209
	v_and_b32_e32 v191, 0xffff0000, v209
	v_fmac_f32_e32 v190, v90, v188
	v_fmac_f32_e32 v191, v91, v189
	v_cvt_pk_bf16_f32 v205, v190, v191
	global_store_dwordx4 v142, v[202:205], s[84:85]
	global_load_dwordx4 v[206:209], v182, s[84:85]
	global_load_dwordx4 v[202:205], v182, s[2:3]
	s_waitcnt vmcnt(19)
	v_lshlrev_b32_e32 v234, 16, v210
	v_and_b32_e32 v235, 0xffff0000, v210
	v_lshlrev_b32_e32 v236, 16, v214
	v_and_b32_e32 v237, 0xffff0000, v214
	v_fmac_f32_e32 v236, v84, v234
	v_fmac_f32_e32 v237, v85, v235
	v_cvt_pk_bf16_f32 v210, v236, v237
	v_lshlrev_b32_e32 v244, 16, v211
	v_and_b32_e32 v245, 0xffff0000, v211
	v_lshlrev_b32_e32 v246, 16, v215
	v_and_b32_e32 v247, 0xffff0000, v215
	v_fmac_f32_e32 v246, v86, v244
	v_fmac_f32_e32 v247, v87, v245
	v_cvt_pk_bf16_f32 v211, v246, v247
	v_lshlrev_b32_e32 v248, 16, v212
	v_and_b32_e32 v249, 0xffff0000, v212
	v_lshlrev_b32_e32 v250, 16, v216
	v_and_b32_e32 v251, 0xffff0000, v216
	v_fmac_f32_e32 v250, v80, v248
	v_fmac_f32_e32 v251, v81, v249
	v_cvt_pk_bf16_f32 v212, v250, v251
	v_lshlrev_b32_e32 v188, 16, v213
	v_and_b32_e32 v189, 0xffff0000, v213
	v_lshlrev_b32_e32 v190, 16, v217
	v_and_b32_e32 v191, 0xffff0000, v217
	v_fmac_f32_e32 v190, v82, v188
	v_fmac_f32_e32 v191, v83, v189
	v_cvt_pk_bf16_f32 v213, v190, v191
	global_store_dwordx4 v142, v[210:213], s[84:85] offset:256
	global_load_dwordx4 v[214:217], v182, s[84:85] offset:256
	global_load_dwordx4 v[210:213], v182, s[2:3] offset:256
	s_waitcnt vmcnt(20)
	v_lshlrev_b32_e32 v234, 16, v218
	v_and_b32_e32 v235, 0xffff0000, v218
	v_lshlrev_b32_e32 v236, 16, v222
	v_and_b32_e32 v237, 0xffff0000, v222
	v_fmac_f32_e32 v236, v76, v234
	v_fmac_f32_e32 v237, v77, v235
	v_cvt_pk_bf16_f32 v218, v236, v237
	v_lshlrev_b32_e32 v244, 16, v219
	v_and_b32_e32 v245, 0xffff0000, v219
	v_lshlrev_b32_e32 v246, 16, v223
	v_and_b32_e32 v247, 0xffff0000, v223
	v_fmac_f32_e32 v246, v78, v244
	v_fmac_f32_e32 v247, v79, v245
	v_cvt_pk_bf16_f32 v219, v246, v247
	v_lshlrev_b32_e32 v248, 16, v220
	v_and_b32_e32 v249, 0xffff0000, v220
	v_lshlrev_b32_e32 v250, 16, v224
	v_and_b32_e32 v251, 0xffff0000, v224
	v_fmac_f32_e32 v250, v72, v248
	v_fmac_f32_e32 v251, v73, v249
	v_cvt_pk_bf16_f32 v220, v250, v251
	v_lshlrev_b32_e32 v188, 16, v221
	v_and_b32_e32 v189, 0xffff0000, v221
	v_lshlrev_b32_e32 v190, 16, v225
	v_and_b32_e32 v191, 0xffff0000, v225
	v_fmac_f32_e32 v190, v74, v188
	v_fmac_f32_e32 v191, v75, v189
	v_cvt_pk_bf16_f32 v221, v190, v191
	global_store_dwordx4 v143, v[218:221], s[84:85]
	global_load_dwordx4 v[222:225], v183, s[84:85]
	global_load_dwordx4 v[218:221], v183, s[2:3]
	s_waitcnt vmcnt(21)
	v_lshlrev_b32_e32 v234, 16, v226
	v_and_b32_e32 v235, 0xffff0000, v226
	v_lshlrev_b32_e32 v236, 16, v230
	v_and_b32_e32 v237, 0xffff0000, v230
	v_fmac_f32_e32 v236, v68, v234
	v_fmac_f32_e32 v237, v69, v235
	v_cvt_pk_bf16_f32 v226, v236, v237
	v_lshlrev_b32_e32 v244, 16, v227
	v_and_b32_e32 v245, 0xffff0000, v227
	v_lshlrev_b32_e32 v246, 16, v231
	v_and_b32_e32 v247, 0xffff0000, v231
	v_fmac_f32_e32 v246, v70, v244
	v_fmac_f32_e32 v247, v71, v245
	v_cvt_pk_bf16_f32 v227, v246, v247
	v_lshlrev_b32_e32 v248, 16, v228
	v_and_b32_e32 v249, 0xffff0000, v228
	v_lshlrev_b32_e32 v250, 16, v232
	v_and_b32_e32 v251, 0xffff0000, v232
	v_fmac_f32_e32 v250, v64, v248
	v_fmac_f32_e32 v251, v65, v249
	v_cvt_pk_bf16_f32 v228, v250, v251
	v_lshlrev_b32_e32 v188, 16, v229
	v_and_b32_e32 v189, 0xffff0000, v229
	v_lshlrev_b32_e32 v190, 16, v233
	v_and_b32_e32 v191, 0xffff0000, v233
	v_fmac_f32_e32 v190, v66, v188
	v_fmac_f32_e32 v191, v67, v189
	v_cvt_pk_bf16_f32 v229, v190, v191
	global_store_dwordx4 v143, v[226:229], s[84:85] offset:256
	global_load_dwordx4 v[230:233], v183, s[84:85] offset:256
	global_load_dwordx4 v[226:229], v183, s[2:3] offset:256
	s_waitcnt vmcnt(21)
	v_lshlrev_b32_e32 v234, 16, v146
	v_and_b32_e32 v235, 0xffff0000, v146
	v_lshlrev_b32_e32 v236, 16, v150
	v_and_b32_e32 v237, 0xffff0000, v150
	v_fmac_f32_e32 v236, v60, v234
	v_fmac_f32_e32 v237, v61, v235
	v_cvt_pk_bf16_f32 v146, v236, v237
	v_lshlrev_b32_e32 v244, 16, v147
	v_and_b32_e32 v245, 0xffff0000, v147
	v_lshlrev_b32_e32 v246, 16, v151
	v_and_b32_e32 v247, 0xffff0000, v151
	v_fmac_f32_e32 v246, v62, v244
	v_fmac_f32_e32 v247, v63, v245
	v_cvt_pk_bf16_f32 v147, v246, v247
	v_lshlrev_b32_e32 v248, 16, v148
	v_and_b32_e32 v249, 0xffff0000, v148
	v_lshlrev_b32_e32 v250, 16, v152
	v_and_b32_e32 v251, 0xffff0000, v152
	v_fmac_f32_e32 v250, v56, v248
	v_fmac_f32_e32 v251, v57, v249
	v_cvt_pk_bf16_f32 v148, v250, v251
	v_lshlrev_b32_e32 v188, 16, v149
	v_and_b32_e32 v189, 0xffff0000, v149
	v_lshlrev_b32_e32 v190, 16, v153
	v_and_b32_e32 v191, 0xffff0000, v153
	v_fmac_f32_e32 v190, v58, v188
	v_fmac_f32_e32 v191, v59, v189
	v_cvt_pk_bf16_f32 v149, v190, v191
	global_store_dwordx4 v144, v[146:149], s[84:85]
	s_waitcnt vmcnt(19)
; __device__ __forceinline__ float bf_lo(unsigned u) { return __uint_as_float(u << 16); }
; __device__ __forceinline__ float bf_hi(unsigned u) { return __uint_as_float(u & 0xffff0000u); }
; __device__ __forceinline__ u32x4 pk8(const f32x4& a, const f32x4& b) { u32x4 w; w.x = pk(a[0], a[1]); w.y = pk(a[2], a[3]); w.z = pk(b[0], b[1]); w.w = pk(b[2], b[3]); return w; }
;     __device__ __forceinline__ void operator()(const f32x4 (&acc)[2][2][4][2], const pg8::Unit& u, int wr, int wc, int fr, int fq) const { if (u.job) kv(acc, u, wr, wc, fr, fq); else q(acc, u, wr, wc, fr, fq); }
;     __device__ __forceinline__ void operator()(const f32x4 (&acc)[2][2][4][2], const pg8::Unit& u, int wr, int wc, int fr, int fq) const { if (u.job) e1(acc, u, wr, wc, fr, fq); else e0(acc, u, wr, wc, fr, fq); }
;     __device__ __forceinline__ void operator()(const f32x4 (&acc)[2][2][4][2], const pg8::Unit& u, int wr, int wc, int fr, int fq) const {
;         const int row0 = u.pm * 256 + wr * 64 + fr; const int col0 = u.pn * 256 + wc * 32 + 8 * fq;
; #pragma unroll
;         for (int ai = 0; ai < 2; ++ai)
; #pragma unroll
;             for (int m = 0; m < 4; ++m)
; #pragma unroll
;                 for (int bj = 0; bj < 2; ++bj) {
;                     const size_t off = (size_t)(row0 + ai * 128 + m * 16) * 2048 + col0 + bj * 128;
;                     const u32x4 g = *(const u32x4*)(G + off);
;                     f32x4 v0 = acc[ai][bj][m][0], v1 = acc[ai][bj][m][1];
;                     v0[0] *= bf_lo(g.x); v0[1] *= bf_hi(g.x); v0[2] *= bf_lo(g.y); v0[3] *= bf_hi(g.y);
;                     v1[0] *= bf_lo(g.z); v1[1] *= bf_hi(g.z); v1[2] *= bf_lo(g.w); v1[3] *= bf_hi(g.w);
;                     if (!first) { const u32x4 p = *(const u32x4*)(Mg + off);
;                         v0[0] += bf_lo(p.x); v0[1] += bf_hi(p.x); v0[2] += bf_lo(p.y); v0[3] += bf_hi(p.y);
;                         v1[0] += bf_lo(p.z); v1[1] += bf_hi(p.z); v1[2] += bf_lo(p.w); v1[3] += bf_hi(p.w); }
;                     *(u32x4*)(Mg + off) = pk8(v0, v1);
;                 }
	v_lshlrev_b32_e32 v234, 16, v154
	v_and_b32_e32 v235, 0xffff0000, v154
	v_lshlrev_b32_e32 v236, 16, v162
	v_and_b32_e32 v237, 0xffff0000, v162
	v_fmac_f32_e32 v236, v52, v234
	v_fmac_f32_e32 v237, v53, v235
	v_cvt_pk_bf16_f32 v154, v236, v237
	v_lshlrev_b32_e32 v244, 16, v155
	v_and_b32_e32 v245, 0xffff0000, v155
	v_lshlrev_b32_e32 v246, 16, v163
	v_and_b32_e32 v247, 0xffff0000, v163
	v_fmac_f32_e32 v246, v54, v244
	v_fmac_f32_e32 v247, v55, v245
	v_cvt_pk_bf16_f32 v155, v246, v247
	v_lshlrev_b32_e32 v248, 16, v156
	v_and_b32_e32 v249, 0xffff0000, v156
	v_lshlrev_b32_e32 v250, 16, v164
	v_and_b32_e32 v251, 0xffff0000, v164
	v_fmac_f32_e32 v250, v48, v248
	v_fmac_f32_e32 v251, v49, v249
	v_cvt_pk_bf16_f32 v156, v250, v251
	v_lshlrev_b32_e32 v188, 16, v157
	v_and_b32_e32 v189, 0xffff0000, v157
	v_lshlrev_b32_e32 v190, 16, v165
	v_and_b32_e32 v191, 0xffff0000, v165
	v_fmac_f32_e32 v190, v50, v188
	v_fmac_f32_e32 v191, v51, v189
	v_cvt_pk_bf16_f32 v157, v190, v191
	global_store_dwordx4 v144, v[154:157], s[84:85] offset:256
	s_waitcnt vmcnt(17)
	v_lshlrev_b32_e32 v234, 16, v166
	v_and_b32_e32 v235, 0xffff0000, v166
	v_lshlrev_b32_e32 v236, 16, v170
	v_and_b32_e32 v237, 0xffff0000, v170
	v_fmac_f32_e32 v236, v44, v234
	v_fmac_f32_e32 v237, v45, v235
	v_cvt_pk_bf16_f32 v166, v236, v237
	v_lshlrev_b32_e32 v244, 16, v167
	v_and_b32_e32 v245, 0xffff0000, v167
	v_lshlrev_b32_e32 v246, 16, v171
	v_and_b32_e32 v247, 0xffff0000, v171
	v_fmac_f32_e32 v246, v46, v244
	v_fmac_f32_e32 v247, v47, v245
	v_cvt_pk_bf16_f32 v167, v246, v247
	v_lshlrev_b32_e32 v248, 16, v168
	v_and_b32_e32 v249, 0xffff0000, v168
	v_lshlrev_b32_e32 v250, 16, v172
	v_and_b32_e32 v251, 0xffff0000, v172
	v_fmac_f32_e32 v250, v40, v248
	v_fmac_f32_e32 v251, v41, v249
	v_cvt_pk_bf16_f32 v168, v250, v251
	v_lshlrev_b32_e32 v188, 16, v169
	v_and_b32_e32 v189, 0xffff0000, v169
	v_lshlrev_b32_e32 v190, 16, v173
	v_and_b32_e32 v191, 0xffff0000, v173
	v_fmac_f32_e32 v190, v42, v188
	v_fmac_f32_e32 v191, v43, v189
	v_cvt_pk_bf16_f32 v169, v190, v191
	global_store_dwordx4 v145, v[166:169], s[84:85]
	s_waitcnt vmcnt(15)
	v_lshlrev_b32_e32 v234, 16, v174
	v_and_b32_e32 v235, 0xffff0000, v174
	v_lshlrev_b32_e32 v236, 16, v178
	v_and_b32_e32 v237, 0xffff0000, v178
	v_fmac_f32_e32 v236, v36, v234
	v_fmac_f32_e32 v237, v37, v235
	v_cvt_pk_bf16_f32 v174, v236, v237
	v_lshlrev_b32_e32 v244, 16, v175
	v_and_b32_e32 v245, 0xffff0000, v175
	v_lshlrev_b32_e32 v246, 16, v179
	v_and_b32_e32 v247, 0xffff0000, v179
	v_fmac_f32_e32 v246, v38, v244
	v_fmac_f32_e32 v247, v39, v245
	v_cvt_pk_bf16_f32 v175, v246, v247
	v_lshlrev_b32_e32 v248, 16, v176
	v_and_b32_e32 v249, 0xffff0000, v176
	v_lshlrev_b32_e32 v250, 16, v180
	v_and_b32_e32 v251, 0xffff0000, v180
	v_fmac_f32_e32 v250, v32, v248
	v_fmac_f32_e32 v251, v33, v249
	v_cvt_pk_bf16_f32 v176, v250, v251
	v_lshlrev_b32_e32 v188, 16, v177
	v_and_b32_e32 v189, 0xffff0000, v177
	v_lshlrev_b32_e32 v190, 16, v181
	v_and_b32_e32 v191, 0xffff0000, v181
	v_fmac_f32_e32 v190, v34, v188
	v_fmac_f32_e32 v191, v35, v189
	v_cvt_pk_bf16_f32 v177, v190, v191
	global_store_dwordx4 v145, v[174:177], s[84:85] offset:256
	s_waitcnt vmcnt(13)
	v_lshlrev_b32_e32 v234, 16, v202
	v_and_b32_e32 v235, 0xffff0000, v202
	v_lshlrev_b32_e32 v236, 16, v206
	v_and_b32_e32 v237, 0xffff0000, v206
	v_fmac_f32_e32 v236, v28, v234
	v_fmac_f32_e32 v237, v29, v235
	v_cvt_pk_bf16_f32 v202, v236, v237
	v_lshlrev_b32_e32 v244, 16, v203
	v_and_b32_e32 v245, 0xffff0000, v203
	v_lshlrev_b32_e32 v246, 16, v207
	v_and_b32_e32 v247, 0xffff0000, v207
	v_fmac_f32_e32 v246, v30, v244
	v_fmac_f32_e32 v247, v31, v245
	v_cvt_pk_bf16_f32 v203, v246, v247
	v_lshlrev_b32_e32 v248, 16, v204
	v_and_b32_e32 v249, 0xffff0000, v204
	v_lshlrev_b32_e32 v250, 16, v208
	v_and_b32_e32 v251, 0xffff0000, v208
	v_fmac_f32_e32 v250, v24, v248
	v_fmac_f32_e32 v251, v25, v249
	v_cvt_pk_bf16_f32 v204, v250, v251
	v_lshlrev_b32_e32 v188, 16, v205
	v_and_b32_e32 v189, 0xffff0000, v205
	v_lshlrev_b32_e32 v190, 16, v209
	v_and_b32_e32 v191, 0xffff0000, v209
	v_fmac_f32_e32 v190, v26, v188
	v_fmac_f32_e32 v191, v27, v189
	v_cvt_pk_bf16_f32 v205, v190, v191
	global_store_dwordx4 v182, v[202:205], s[84:85]
	s_waitcnt vmcnt(11)
	v_lshlrev_b32_e32 v234, 16, v210
	v_and_b32_e32 v235, 0xffff0000, v210
	v_lshlrev_b32_e32 v236, 16, v214
	v_and_b32_e32 v237, 0xffff0000, v214
	v_fmac_f32_e32 v236, v20, v234
	v_fmac_f32_e32 v237, v21, v235
	v_cvt_pk_bf16_f32 v210, v236, v237
	v_lshlrev_b32_e32 v244, 16, v211
	v_and_b32_e32 v245, 0xffff0000, v211
	v_lshlrev_b32_e32 v246, 16, v215
	v_and_b32_e32 v247, 0xffff0000, v215
	v_fmac_f32_e32 v246, v22, v244
	v_fmac_f32_e32 v247, v23, v245
	v_cvt_pk_bf16_f32 v211, v246, v247
	v_lshlrev_b32_e32 v248, 16, v212
	v_and_b32_e32 v249, 0xffff0000, v212
	v_lshlrev_b32_e32 v250, 16, v216
	v_and_b32_e32 v251, 0xffff0000, v216
	v_fmac_f32_e32 v250, v16, v248
	v_fmac_f32_e32 v251, v17, v249
	v_cvt_pk_bf16_f32 v212, v250, v251
	v_lshlrev_b32_e32 v188, 16, v213
	v_and_b32_e32 v189, 0xffff0000, v213
	v_lshlrev_b32_e32 v190, 16, v217
	v_and_b32_e32 v191, 0xffff0000, v217
	v_fmac_f32_e32 v190, v18, v188
	v_fmac_f32_e32 v191, v19, v189
	v_cvt_pk_bf16_f32 v213, v190, v191
	global_store_dwordx4 v182, v[210:213], s[84:85] offset:256
	s_waitcnt vmcnt(9)
; __device__ __forceinline__ float bf_lo(unsigned u) { return __uint_as_float(u << 16); }
; __device__ __forceinline__ float bf_hi(unsigned u) { return __uint_as_float(u & 0xffff0000u); }
; __device__ __forceinline__ u32x4 pk8(const f32x4& a, const f32x4& b) { u32x4 w; w.x = pk(a[0], a[1]); w.y = pk(a[2], a[3]); w.z = pk(b[0], b[1]); w.w = pk(b[2], b[3]); return w; }
;     __device__ __forceinline__ void operator()(const f32x4 (&acc)[2][2][4][2], const pg8::Unit& u, int wr, int wc, int fr, int fq) const { if (u.job) kv(acc, u, wr, wc, fr, fq); else q(acc, u, wr, wc, fr, fq); }
;     __device__ __forceinline__ void operator()(const f32x4 (&acc)[2][2][4][2], const pg8::Unit& u, int wr, int wc, int fr, int fq) const { if (u.job) e1(acc, u, wr, wc, fr, fq); else e0(acc, u, wr, wc, fr, fq); }
;     __device__ __forceinline__ void operator()(const f32x4 (&acc)[2][2][4][2], const pg8::Unit& u, int wr, int wc, int fr, int fq) const {
;         const int row0 = u.pm * 256 + wr * 64 + fr; const int col0 = u.pn * 256 + wc * 32 + 8 * fq;
; #pragma unroll
;         for (int ai = 0; ai < 2; ++ai)
; #pragma unroll
;             for (int m = 0; m < 4; ++m)
; #pragma unroll
;                 for (int bj = 0; bj < 2; ++bj) {
;                     const size_t off = (size_t)(row0 + ai * 128 + m * 16) * 2048 + col0 + bj * 128;
;                     const u32x4 g = *(const u32x4*)(G + off);
;                     f32x4 v0 = acc[ai][bj][m][0], v1 = acc[ai][bj][m][1];
;                     v0[0] *= bf_lo(g.x); v0[1] *= bf_hi(g.x); v0[2] *= bf_lo(g.y); v0[3] *= bf_hi(g.y);
;                     v1[0] *= bf_lo(g.z); v1[1] *= bf_hi(g.z); v1[2] *= bf_lo(g.w); v1[3] *= bf_hi(g.w);
;                     if (!first) { const u32x4 p = *(const u32x4*)(Mg + off);
;                         v0[0] += bf_lo(p.x); v0[1] += bf_hi(p.x); v0[2] += bf_lo(p.y); v0[3] += bf_hi(p.y);
;                         v1[0] += bf_lo(p.z); v1[1] += bf_hi(p.z); v1[2] += bf_lo(p.w); v1[3] += bf_hi(p.w); }
;                     *(u32x4*)(Mg + off) = pk8(v0, v1);
;                 }
	v_lshlrev_b32_e32 v234, 16, v218
	v_and_b32_e32 v235, 0xffff0000, v218
	v_lshlrev_b32_e32 v236, 16, v222
	v_and_b32_e32 v237, 0xffff0000, v222
	v_fmac_f32_e32 v236, v12, v234
	v_fmac_f32_e32 v237, v13, v235
	v_cvt_pk_bf16_f32 v218, v236, v237
	v_lshlrev_b32_e32 v244, 16, v219
	v_and_b32_e32 v245, 0xffff0000, v219
	v_lshlrev_b32_e32 v246, 16, v223
	v_and_b32_e32 v247, 0xffff0000, v223
	v_fmac_f32_e32 v246, v14, v244
	v_fmac_f32_e32 v247, v15, v245
	v_cvt_pk_bf16_f32 v219, v246, v247
	v_lshlrev_b32_e32 v248, 16, v220
	v_and_b32_e32 v249, 0xffff0000, v220
	v_lshlrev_b32_e32 v250, 16, v224
	v_and_b32_e32 v251, 0xffff0000, v224
	v_fmac_f32_e32 v250, v8, v248
	v_fmac_f32_e32 v251, v9, v249
	v_cvt_pk_bf16_f32 v220, v250, v251
	v_lshlrev_b32_e32 v188, 16, v221
	v_and_b32_e32 v189, 0xffff0000, v221
	v_lshlrev_b32_e32 v190, 16, v225
	v_and_b32_e32 v191, 0xffff0000, v225
	v_fmac_f32_e32 v190, v10, v188
	v_fmac_f32_e32 v191, v11, v189
	v_cvt_pk_bf16_f32 v221, v190, v191
	global_store_dwordx4 v183, v[218:221], s[84:85]
	s_waitcnt vmcnt(7)
	v_lshlrev_b32_e32 v234, 16, v226
	v_and_b32_e32 v235, 0xffff0000, v226
	v_lshlrev_b32_e32 v236, 16, v230
	v_and_b32_e32 v237, 0xffff0000, v230
	v_fmac_f32_e32 v236, v4, v234
	v_fmac_f32_e32 v237, v5, v235
	v_cvt_pk_bf16_f32 v226, v236, v237
	v_lshlrev_b32_e32 v244, 16, v227
	v_and_b32_e32 v245, 0xffff0000, v227
	v_lshlrev_b32_e32 v246, 16, v231
	v_and_b32_e32 v247, 0xffff0000, v231
	v_fmac_f32_e32 v246, v6, v244
	v_fmac_f32_e32 v247, v7, v245
	v_cvt_pk_bf16_f32 v227, v246, v247
	v_lshlrev_b32_e32 v248, 16, v228
	v_and_b32_e32 v249, 0xffff0000, v228
	v_lshlrev_b32_e32 v250, 16, v232
	v_and_b32_e32 v251, 0xffff0000, v232
	v_fmac_f32_e32 v250, v0, v248
	v_fmac_f32_e32 v251, v1, v249
	v_cvt_pk_bf16_f32 v228, v250, v251
	v_lshlrev_b32_e32 v188, 16, v229
	v_and_b32_e32 v189, 0xffff0000, v229
	v_lshlrev_b32_e32 v190, 16, v233
	v_and_b32_e32 v191, 0xffff0000, v233
	v_fmac_f32_e32 v190, v2, v188
	v_fmac_f32_e32 v191, v3, v189
	v_cvt_pk_bf16_f32 v229, v190, v191
	global_store_dwordx4 v183, v[226:229], s[84:85] offset:256
	s_mov_b64 s[22:23], 0xb0100
	s_branch .LBB0_1154
.LBB0_1153:
	v_readlane_b32 s2, v252, 56
	v_readlane_b32 s3, v252, 57
	s_nop 4
	global_load_dwordx4 v[146:149], v140, s[2:3]
	global_load_dwordx4 v[150:153], v140, s[2:3] offset:256
	global_load_dwordx4 v[154:157], v141, s[2:3]
	global_load_dwordx4 v[162:165], v141, s[2:3] offset:256
	global_load_dwordx4 v[166:169], v142, s[2:3]
	global_load_dwordx4 v[170:173], v142, s[2:3] offset:256
	global_load_dwordx4 v[174:177], v143, s[2:3]
	global_load_dwordx4 v[178:181], v143, s[2:3] offset:256
	global_load_dwordx4 v[202:205], v144, s[2:3]
	global_load_dwordx4 v[206:209], v144, s[2:3] offset:256
	global_load_dwordx4 v[210:213], v145, s[2:3]
	global_load_dwordx4 v[214:217], v145, s[2:3] offset:256
	global_load_dwordx4 v[218:221], v182, s[2:3]
	global_load_dwordx4 v[222:225], v182, s[2:3] offset:256
	global_load_dwordx4 v[226:229], v183, s[2:3]
	global_load_dwordx4 v[230:233], v183, s[2:3] offset:256
	s_waitcnt vmcnt(15)
	v_lshlrev_b32_e32 v234, 16, v146
	v_and_b32_e32 v235, 0xffff0000, v146
	v_mul_f32_e32 v234, v124, v234
	v_mul_f32_e32 v235, v125, v235
	v_cvt_pk_bf16_f32 v146, v234, v235
	v_lshlrev_b32_e32 v236, 16, v147
	v_and_b32_e32 v237, 0xffff0000, v147
	v_mul_f32_e32 v236, v126, v236
	v_mul_f32_e32 v237, v127, v237
	v_cvt_pk_bf16_f32 v147, v236, v237
	v_lshlrev_b32_e32 v244, 16, v148
	v_and_b32_e32 v245, 0xffff0000, v148
	v_mul_f32_e32 v244, v120, v244
	v_mul_f32_e32 v245, v121, v245
	v_cvt_pk_bf16_f32 v148, v244, v245
	v_lshlrev_b32_e32 v246, 16, v149
	v_and_b32_e32 v247, 0xffff0000, v149
	v_mul_f32_e32 v246, v122, v246
	v_mul_f32_e32 v247, v123, v247
	v_cvt_pk_bf16_f32 v149, v246, v247
	global_store_dwordx4 v140, v[146:149], s[84:85]
	s_waitcnt vmcnt(15)
	v_lshlrev_b32_e32 v234, 16, v150
	v_and_b32_e32 v235, 0xffff0000, v150
	v_mul_f32_e32 v234, v116, v234
	v_mul_f32_e32 v235, v117, v235
	v_cvt_pk_bf16_f32 v150, v234, v235
	v_lshlrev_b32_e32 v236, 16, v151
	v_and_b32_e32 v237, 0xffff0000, v151
	v_mul_f32_e32 v236, v118, v236
	v_mul_f32_e32 v237, v119, v237
	v_cvt_pk_bf16_f32 v151, v236, v237
	v_lshlrev_b32_e32 v244, 16, v152
	v_and_b32_e32 v245, 0xffff0000, v152
	v_mul_f32_e32 v244, v112, v244
	v_mul_f32_e32 v245, v113, v245
	v_cvt_pk_bf16_f32 v152, v244, v245
	v_lshlrev_b32_e32 v246, 16, v153
	v_and_b32_e32 v247, 0xffff0000, v153
	v_mul_f32_e32 v246, v114, v246
	v_mul_f32_e32 v247, v115, v247
	v_cvt_pk_bf16_f32 v153, v246, v247
	global_store_dwordx4 v140, v[150:153], s[84:85] offset:256
	s_waitcnt vmcnt(15)
	v_lshlrev_b32_e32 v234, 16, v154
	v_and_b32_e32 v235, 0xffff0000, v154
	v_mul_f32_e32 v234, v108, v234
	v_mul_f32_e32 v235, v109, v235
	v_cvt_pk_bf16_f32 v154, v234, v235
	v_lshlrev_b32_e32 v236, 16, v155
	v_and_b32_e32 v237, 0xffff0000, v155
	v_mul_f32_e32 v236, v110, v236
	v_mul_f32_e32 v237, v111, v237
	v_cvt_pk_bf16_f32 v155, v236, v237
	v_lshlrev_b32_e32 v244, 16, v156
	v_and_b32_e32 v245, 0xffff0000, v156
	v_mul_f32_e32 v244, v104, v244
	v_mul_f32_e32 v245, v105, v245
	v_cvt_pk_bf16_f32 v156, v244, v245
	v_lshlrev_b32_e32 v246, 16, v157
	v_and_b32_e32 v247, 0xffff0000, v157
	v_mul_f32_e32 v246, v106, v246
	v_mul_f32_e32 v247, v107, v247
	v_cvt_pk_bf16_f32 v157, v246, v247
	global_store_dwordx4 v141, v[154:157], s[84:85]
	s_waitcnt vmcnt(15)
; __device__ __forceinline__ float bf_lo(unsigned u) { return __uint_as_float(u << 16); }
; __device__ __forceinline__ float bf_hi(unsigned u) { return __uint_as_float(u & 0xffff0000u); }
; __device__ __forceinline__ u32x4 pk8(const f32x4& a, const f32x4& b) { u32x4 w; w.x = pk(a[0], a[1]); w.y = pk(a[2], a[3]); w.z = pk(b[0], b[1]); w.w = pk(b[2], b[3]); return w; }
;     __device__ __forceinline__ void operator()(const f32x4 (&acc)[2][2][4][2], const pg8::Unit& u, int wr, int wc, int fr, int fq) const {
;     ...
;                     v0[0] *= bf_lo(g.x); v0[1] *= bf_hi(g.x); v0[2] *= bf_lo(g.y); v0[3] *= bf_hi(g.y);
;                     v1[0] *= bf_lo(g.z); v1[1] *= bf_hi(g.z); v1[2] *= bf_lo(g.w); v1[3] *= bf_hi(g.w);
;                     if (!first) { const u32x4 p = *(const u32x4*)(Mg + off);
;                         v0[0] += bf_lo(p.x); v0[1] += bf_hi(p.x); v0[2] += bf_lo(p.y); v0[3] += bf_hi(p.y);
;                         v1[0] += bf_lo(p.z); v1[1] += bf_hi(p.z); v1[2] += bf_lo(p.w); v1[3] += bf_hi(p.w); }
;                     *(u32x4*)(Mg + off) = pk8(v0, v1);
	v_lshlrev_b32_e32 v234, 16, v162
	v_and_b32_e32 v235, 0xffff0000, v162
	v_mul_f32_e32 v234, v100, v234
	v_mul_f32_e32 v235, v101, v235
	v_cvt_pk_bf16_f32 v162, v234, v235
	v_lshlrev_b32_e32 v236, 16, v163
	v_and_b32_e32 v237, 0xffff0000, v163
	v_mul_f32_e32 v236, v102, v236
	v_mul_f32_e32 v237, v103, v237
	v_cvt_pk_bf16_f32 v163, v236, v237
	v_lshlrev_b32_e32 v244, 16, v164
	v_and_b32_e32 v245, 0xffff0000, v164
	v_mul_f32_e32 v244, v96, v244
	v_mul_f32_e32 v245, v97, v245
	v_cvt_pk_bf16_f32 v164, v244, v245
	v_lshlrev_b32_e32 v246, 16, v165
	v_and_b32_e32 v247, 0xffff0000, v165
	v_mul_f32_e32 v246, v98, v246
	v_mul_f32_e32 v247, v99, v247
	v_cvt_pk_bf16_f32 v165, v246, v247
	global_store_dwordx4 v141, v[162:165], s[84:85] offset:256
	s_waitcnt vmcnt(15)
	v_lshlrev_b32_e32 v234, 16, v166
	v_and_b32_e32 v235, 0xffff0000, v166
	v_mul_f32_e32 v234, v92, v234
	v_mul_f32_e32 v235, v93, v235
	v_cvt_pk_bf16_f32 v166, v234, v235
	v_lshlrev_b32_e32 v236, 16, v167
	v_and_b32_e32 v237, 0xffff0000, v167
	v_mul_f32_e32 v236, v94, v236
	v_mul_f32_e32 v237, v95, v237
	v_cvt_pk_bf16_f32 v167, v236, v237
	v_lshlrev_b32_e32 v244, 16, v168
	v_and_b32_e32 v245, 0xffff0000, v168
	v_mul_f32_e32 v244, v88, v244
	v_mul_f32_e32 v245, v89, v245
	v_cvt_pk_bf16_f32 v168, v244, v245
	v_lshlrev_b32_e32 v246, 16, v169
	v_and_b32_e32 v247, 0xffff0000, v169
	v_mul_f32_e32 v246, v90, v246
	v_mul_f32_e32 v247, v91, v247
	v_cvt_pk_bf16_f32 v169, v246, v247
	global_store_dwordx4 v142, v[166:169], s[84:85]
	s_waitcnt vmcnt(15)
	v_lshlrev_b32_e32 v234, 16, v170
	v_and_b32_e32 v235, 0xffff0000, v170
	v_mul_f32_e32 v234, v84, v234
	v_mul_f32_e32 v235, v85, v235
	v_cvt_pk_bf16_f32 v170, v234, v235
	v_lshlrev_b32_e32 v236, 16, v171
	v_and_b32_e32 v237, 0xffff0000, v171
	v_mul_f32_e32 v236, v86, v236
	v_mul_f32_e32 v237, v87, v237
	v_cvt_pk_bf16_f32 v171, v236, v237
	v_lshlrev_b32_e32 v244, 16, v172
	v_and_b32_e32 v245, 0xffff0000, v172
	v_mul_f32_e32 v244, v80, v244
	v_mul_f32_e32 v245, v81, v245
	v_cvt_pk_bf16_f32 v172, v244, v245
	v_lshlrev_b32_e32 v246, 16, v173
	v_and_b32_e32 v247, 0xffff0000, v173
	v_mul_f32_e32 v246, v82, v246
	v_mul_f32_e32 v247, v83, v247
	v_cvt_pk_bf16_f32 v173, v246, v247
	global_store_dwordx4 v142, v[170:173], s[84:85] offset:256
	s_waitcnt vmcnt(15)
	v_lshlrev_b32_e32 v234, 16, v174
	v_and_b32_e32 v235, 0xffff0000, v174
	v_mul_f32_e32 v234, v76, v234
	v_mul_f32_e32 v235, v77, v235
	v_cvt_pk_bf16_f32 v174, v234, v235
	v_lshlrev_b32_e32 v236, 16, v175
	v_and_b32_e32 v237, 0xffff0000, v175
	v_mul_f32_e32 v236, v78, v236
	v_mul_f32_e32 v237, v79, v237
	v_cvt_pk_bf16_f32 v175, v236, v237
	v_lshlrev_b32_e32 v244, 16, v176
	v_and_b32_e32 v245, 0xffff0000, v176
	v_mul_f32_e32 v244, v72, v244
	v_mul_f32_e32 v245, v73, v245
	v_cvt_pk_bf16_f32 v176, v244, v245
	v_lshlrev_b32_e32 v246, 16, v177
	v_and_b32_e32 v247, 0xffff0000, v177
	v_mul_f32_e32 v246, v74, v246
	v_mul_f32_e32 v247, v75, v247
	v_cvt_pk_bf16_f32 v177, v246, v247
	global_store_dwordx4 v143, v[174:177], s[84:85]
	s_waitcnt vmcnt(15)
	v_lshlrev_b32_e32 v234, 16, v178
	v_and_b32_e32 v235, 0xffff0000, v178
	v_mul_f32_e32 v234, v68, v234
	v_mul_f32_e32 v235, v69, v235
	v_cvt_pk_bf16_f32 v178, v234, v235
	v_lshlrev_b32_e32 v236, 16, v179
	v_and_b32_e32 v237, 0xffff0000, v179
	v_mul_f32_e32 v236, v70, v236
	v_mul_f32_e32 v237, v71, v237
	v_cvt_pk_bf16_f32 v179, v236, v237
	v_lshlrev_b32_e32 v244, 16, v180
	v_and_b32_e32 v245, 0xffff0000, v180
	v_mul_f32_e32 v244, v64, v244
	v_mul_f32_e32 v245, v65, v245
	v_cvt_pk_bf16_f32 v180, v244, v245
	v_lshlrev_b32_e32 v246, 16, v181
	v_and_b32_e32 v247, 0xffff0000, v181
	v_mul_f32_e32 v246, v66, v246
	v_mul_f32_e32 v247, v67, v247
	v_cvt_pk_bf16_f32 v181, v246, v247
	global_store_dwordx4 v143, v[178:181], s[84:85] offset:256
	s_waitcnt vmcnt(15)
	v_lshlrev_b32_e32 v234, 16, v202
	v_and_b32_e32 v235, 0xffff0000, v202
	v_mul_f32_e32 v234, v60, v234
	v_mul_f32_e32 v235, v61, v235
	v_cvt_pk_bf16_f32 v202, v234, v235
	v_lshlrev_b32_e32 v236, 16, v203
	v_and_b32_e32 v237, 0xffff0000, v203
	v_mul_f32_e32 v236, v62, v236
	v_mul_f32_e32 v237, v63, v237
	v_cvt_pk_bf16_f32 v203, v236, v237
	v_lshlrev_b32_e32 v244, 16, v204
	v_and_b32_e32 v245, 0xffff0000, v204
	v_mul_f32_e32 v244, v56, v244
	v_mul_f32_e32 v245, v57, v245
	v_cvt_pk_bf16_f32 v204, v244, v245
	v_lshlrev_b32_e32 v246, 16, v205
	v_and_b32_e32 v247, 0xffff0000, v205
	v_mul_f32_e32 v246, v58, v246
	v_mul_f32_e32 v247, v59, v247
	v_cvt_pk_bf16_f32 v205, v246, v247
	global_store_dwordx4 v144, v[202:205], s[84:85]
	s_waitcnt vmcnt(15)
; __device__ __forceinline__ float bf_lo(unsigned u) { return __uint_as_float(u << 16); }
; __device__ __forceinline__ float bf_hi(unsigned u) { return __uint_as_float(u & 0xffff0000u); }
; __device__ __forceinline__ u32x4 pk8(const f32x4& a, const f32x4& b) { u32x4 w; w.x = pk(a[0], a[1]); w.y = pk(a[2], a[3]); w.z = pk(b[0], b[1]); w.w = pk(b[2], b[3]); return w; }
;     __device__ __forceinline__ void operator()(const f32x4 (&acc)[2][2][4][2], const pg8::Unit& u, int wr, int wc, int fr, int fq) const {
;     ...
;                     v0[0] *= bf_lo(g.x); v0[1] *= bf_hi(g.x); v0[2] *= bf_lo(g.y); v0[3] *= bf_hi(g.y);
;                     v1[0] *= bf_lo(g.z); v1[1] *= bf_hi(g.z); v1[2] *= bf_lo(g.w); v1[3] *= bf_hi(g.w);
;                     if (!first) { const u32x4 p = *(const u32x4*)(Mg + off);
;                         v0[0] += bf_lo(p.x); v0[1] += bf_hi(p.x); v0[2] += bf_lo(p.y); v0[3] += bf_hi(p.y);
;                         v1[0] += bf_lo(p.z); v1[1] += bf_hi(p.z); v1[2] += bf_lo(p.w); v1[3] += bf_hi(p.w); }
;                     *(u32x4*)(Mg + off) = pk8(v0, v1);
	v_lshlrev_b32_e32 v234, 16, v206
	v_and_b32_e32 v235, 0xffff0000, v206
	v_mul_f32_e32 v234, v52, v234
	v_mul_f32_e32 v235, v53, v235
	v_cvt_pk_bf16_f32 v206, v234, v235
	v_lshlrev_b32_e32 v236, 16, v207
	v_and_b32_e32 v237, 0xffff0000, v207
	v_mul_f32_e32 v236, v54, v236
	v_mul_f32_e32 v237, v55, v237
	v_cvt_pk_bf16_f32 v207, v236, v237
	v_lshlrev_b32_e32 v244, 16, v208
	v_and_b32_e32 v245, 0xffff0000, v208
	v_mul_f32_e32 v244, v48, v244
	v_mul_f32_e32 v245, v49, v245
	v_cvt_pk_bf16_f32 v208, v244, v245
	v_lshlrev_b32_e32 v246, 16, v209
	v_and_b32_e32 v247, 0xffff0000, v209
	v_mul_f32_e32 v246, v50, v246
	v_mul_f32_e32 v247, v51, v247
	v_cvt_pk_bf16_f32 v209, v246, v247
	global_store_dwordx4 v144, v[206:209], s[84:85] offset:256
	s_waitcnt vmcnt(15)
	v_lshlrev_b32_e32 v234, 16, v210
	v_and_b32_e32 v235, 0xffff0000, v210
	v_mul_f32_e32 v234, v44, v234
	v_mul_f32_e32 v235, v45, v235
	v_cvt_pk_bf16_f32 v210, v234, v235
	v_lshlrev_b32_e32 v236, 16, v211
	v_and_b32_e32 v237, 0xffff0000, v211
	v_mul_f32_e32 v236, v46, v236
	v_mul_f32_e32 v237, v47, v237
	v_cvt_pk_bf16_f32 v211, v236, v237
	v_lshlrev_b32_e32 v244, 16, v212
	v_and_b32_e32 v245, 0xffff0000, v212
	v_mul_f32_e32 v244, v40, v244
	v_mul_f32_e32 v245, v41, v245
	v_cvt_pk_bf16_f32 v212, v244, v245
	v_lshlrev_b32_e32 v246, 16, v213
	v_and_b32_e32 v247, 0xffff0000, v213
	v_mul_f32_e32 v246, v42, v246
	v_mul_f32_e32 v247, v43, v247
	v_cvt_pk_bf16_f32 v213, v246, v247
	global_store_dwordx4 v145, v[210:213], s[84:85]
	s_waitcnt vmcnt(15)
	v_lshlrev_b32_e32 v234, 16, v214
	v_and_b32_e32 v235, 0xffff0000, v214
	v_mul_f32_e32 v234, v36, v234
	v_mul_f32_e32 v235, v37, v235
	v_cvt_pk_bf16_f32 v214, v234, v235
	v_lshlrev_b32_e32 v236, 16, v215
	v_and_b32_e32 v237, 0xffff0000, v215
	v_mul_f32_e32 v236, v38, v236
	v_mul_f32_e32 v237, v39, v237
	v_cvt_pk_bf16_f32 v215, v236, v237
	v_lshlrev_b32_e32 v244, 16, v216
	v_and_b32_e32 v245, 0xffff0000, v216
	v_mul_f32_e32 v244, v32, v244
	v_mul_f32_e32 v245, v33, v245
	v_cvt_pk_bf16_f32 v216, v244, v245
	v_lshlrev_b32_e32 v246, 16, v217
	v_and_b32_e32 v247, 0xffff0000, v217
	v_mul_f32_e32 v246, v34, v246
	v_mul_f32_e32 v247, v35, v247
	v_cvt_pk_bf16_f32 v217, v246, v247
	global_store_dwordx4 v145, v[214:217], s[84:85] offset:256
	s_waitcnt vmcnt(15)
	v_lshlrev_b32_e32 v234, 16, v218
	v_and_b32_e32 v235, 0xffff0000, v218
	v_mul_f32_e32 v234, v28, v234
	v_mul_f32_e32 v235, v29, v235
	v_cvt_pk_bf16_f32 v218, v234, v235
	v_lshlrev_b32_e32 v236, 16, v219
	v_and_b32_e32 v237, 0xffff0000, v219
	v_mul_f32_e32 v236, v30, v236
	v_mul_f32_e32 v237, v31, v237
	v_cvt_pk_bf16_f32 v219, v236, v237
	v_lshlrev_b32_e32 v244, 16, v220
	v_and_b32_e32 v245, 0xffff0000, v220
	v_mul_f32_e32 v244, v24, v244
	v_mul_f32_e32 v245, v25, v245
	v_cvt_pk_bf16_f32 v220, v244, v245
	v_lshlrev_b32_e32 v246, 16, v221
	v_and_b32_e32 v247, 0xffff0000, v221
	v_mul_f32_e32 v246, v26, v246
	v_mul_f32_e32 v247, v27, v247
	v_cvt_pk_bf16_f32 v221, v246, v247
	global_store_dwordx4 v182, v[218:221], s[84:85]
	s_waitcnt vmcnt(15)
	v_lshlrev_b32_e32 v234, 16, v222
	v_and_b32_e32 v235, 0xffff0000, v222
	v_mul_f32_e32 v234, v20, v234
	v_mul_f32_e32 v235, v21, v235
	v_cvt_pk_bf16_f32 v222, v234, v235
	v_lshlrev_b32_e32 v236, 16, v223
	v_and_b32_e32 v237, 0xffff0000, v223
	v_mul_f32_e32 v236, v22, v236
	v_mul_f32_e32 v237, v23, v237
	v_cvt_pk_bf16_f32 v223, v236, v237
	v_lshlrev_b32_e32 v244, 16, v224
	v_and_b32_e32 v245, 0xffff0000, v224
	v_mul_f32_e32 v244, v16, v244
	v_mul_f32_e32 v245, v17, v245
	v_cvt_pk_bf16_f32 v224, v244, v245
	v_lshlrev_b32_e32 v246, 16, v225
	v_and_b32_e32 v247, 0xffff0000, v225
	v_mul_f32_e32 v246, v18, v246
	v_mul_f32_e32 v247, v19, v247
	v_cvt_pk_bf16_f32 v225, v246, v247
	global_store_dwordx4 v182, v[222:225], s[84:85] offset:256
	s_waitcnt vmcnt(15)
	v_lshlrev_b32_e32 v234, 16, v226
	v_and_b32_e32 v235, 0xffff0000, v226
	v_mul_f32_e32 v234, v12, v234
	v_mul_f32_e32 v235, v13, v235
	v_cvt_pk_bf16_f32 v226, v234, v235
	v_lshlrev_b32_e32 v236, 16, v227
	v_and_b32_e32 v237, 0xffff0000, v227
	v_mul_f32_e32 v236, v14, v236
	v_mul_f32_e32 v237, v15, v237
	v_cvt_pk_bf16_f32 v227, v236, v237
	v_lshlrev_b32_e32 v244, 16, v228
	v_and_b32_e32 v245, 0xffff0000, v228
	v_mul_f32_e32 v244, v8, v244
	v_mul_f32_e32 v245, v9, v245
	v_cvt_pk_bf16_f32 v228, v244, v245
	v_lshlrev_b32_e32 v246, 16, v229
	v_and_b32_e32 v247, 0xffff0000, v229
	v_mul_f32_e32 v246, v10, v246
	v_mul_f32_e32 v247, v11, v247
	v_cvt_pk_bf16_f32 v229, v246, v247
	global_store_dwordx4 v183, v[226:229], s[84:85]
	s_waitcnt vmcnt(15)
	v_lshlrev_b32_e32 v234, 16, v230
	v_and_b32_e32 v235, 0xffff0000, v230
	v_mul_f32_e32 v234, v4, v234
	v_mul_f32_e32 v235, v5, v235
	v_cvt_pk_bf16_f32 v230, v234, v235
	v_lshlrev_b32_e32 v236, 16, v231
	v_and_b32_e32 v237, 0xffff0000, v231
	v_mul_f32_e32 v236, v6, v236
	v_mul_f32_e32 v237, v7, v237
	v_cvt_pk_bf16_f32 v231, v236, v237
	v_lshlrev_b32_e32 v244, 16, v232
	v_and_b32_e32 v245, 0xffff0000, v232
	v_mul_f32_e32 v244, v0, v244
	v_mul_f32_e32 v245, v1, v245
	v_cvt_pk_bf16_f32 v232, v244, v245
	v_lshlrev_b32_e32 v246, 16, v233
	v_and_b32_e32 v247, 0xffff0000, v233
	v_mul_f32_e32 v246, v2, v246
	v_mul_f32_e32 v247, v3, v247
	v_cvt_pk_bf16_f32 v233, v246, v247
	global_store_dwordx4 v183, v[230:233], s[84:85] offset:256
	s_mov_b64 s[22:23], 0xb0100

; __device__ __forceinline__ float bf_lo(unsigned u) { return __uint_as_float(u << 16); }
; __device__ __forceinline__ float bf_hi(unsigned u) { return __uint_as_float(u & 0xffff0000u); }
; __device__ __forceinline__ u32x4 pk8(const f32x4& a, const f32x4& b) { u32x4 w; w.x = pk(a[0], a[1]); w.y = pk(a[2], a[3]); w.z = pk(b[0], b[1]); w.w = pk(b[2], b[3]); return w; }
;     __device__ __forceinline__ void operator()(const f32x4 (&acc)[2][2][4][2], const pg8::Unit& u, int wr, int wc, int fr, int fq) const { if (u.job) kv(acc, u, wr, wc, fr, fq); else q(acc, u, wr, wc, fr, fq); }
;     __device__ __forceinline__ void operator()(const f32x4 (&acc)[2][2][4][2], const pg8::Unit& u, int wr, int wc, int fr, int fq) const { if (u.job) e1(acc, u, wr, wc, fr, fq); else e0(acc, u, wr, wc, fr, fq); }
;     __device__ __forceinline__ void operator()(const f32x4 (&acc)[2][2][4][2], const pg8::Unit& u, int wr, int wc, int fr, int fq) const {
;         const int row0 = u.pm * 256 + wr * 64 + fr; const int col0 = u.pn * 256 + wc * 32 + 8 * fq;
; #pragma unroll
;         for (int ai = 0; ai < 2; ++ai)
; #pragma unroll
;             for (int m = 0; m < 4; ++m)
; #pragma unroll
;                 for (int bj = 0; bj < 2; ++bj) {
;                     const size_t off = (size_t)(row0 + ai * 128 + m * 16) * 2048 + col0 + bj * 128;
;                     const u32x4 g = *(const u32x4*)(G + off);
;                     f32x4 v0 = acc[ai][bj][m][0], v1 = acc[ai][bj][m][1];
;                     v0[0] *= bf_lo(g.x); v0[1] *= bf_hi(g.x); v0[2] *= bf_lo(g.y); v0[3] *= bf_hi(g.y);
;                     v1[0] *= bf_lo(g.z); v1[1] *= bf_hi(g.z); v1[2] *= bf_lo(g.w); v1[3] *= bf_hi(g.w);
;                     if (!first) { const u32x4 p = *(const u32x4*)(Mg + off);
;                         v0[0] += bf_lo(p.x); v0[1] += bf_hi(p.x); v0[2] += bf_lo(p.y); v0[3] += bf_hi(p.y);
;                         v1[0] += bf_lo(p.z); v1[1] += bf_hi(p.z); v1[2] += bf_lo(p.w); v1[3] += bf_hi(p.w); }
;                     *(u32x4*)(Mg + off) = pk8(v0, v1);
;                 }
.LBB0_1175:
	v_lshl_add_u32 v193, s3, 8, v146
	v_lshl_or_b32 v140, s2, 8, v148
	v_lshlrev_b32_e32 v140, 1, v140
	v_lshl_add_u32 v140, v193, 12, v140
	v_add_u32_e32 v141, 0x10000, v140
	v_add_u32_e32 v142, 0x20000, v140
	v_add_u32_e32 v143, 0x30000, v140
	v_add_u32_e32 v144, 0x80000, v140
	v_add_u32_e32 v145, 0x90000, v140
	v_add_u32_e32 v182, 0xa0000, v140
	v_add_u32_e32 v183, 0xb0000, v140
	v_readlane_b32 s2, v254, 9
	v_readlane_b32 s3, v254, 10
	s_nop 15
	s_nop 3
	s_andn2_b64 vcc, exec, s[4:5]
	global_load_dwordx4 v[154:157], v140, s[84:85]
	global_load_dwordx4 v[150:153], v140, s[2:3]
	global_load_dwordx4 v[162:165], v140, s[84:85] offset:256
	global_load_dwordx4 v[158:161], v140, s[2:3] offset:256
	global_load_dwordx4 v[170:173], v141, s[84:85]
	global_load_dwordx4 v[166:169], v141, s[2:3]
	global_load_dwordx4 v[178:181], v141, s[84:85] offset:256
	global_load_dwordx4 v[174:177], v141, s[2:3] offset:256
	global_load_dwordx4 v[206:209], v142, s[84:85]
	global_load_dwordx4 v[202:205], v142, s[2:3]
	global_load_dwordx4 v[214:217], v142, s[84:85] offset:256
	global_load_dwordx4 v[210:213], v142, s[2:3] offset:256
	global_load_dwordx4 v[222:225], v143, s[84:85]
	global_load_dwordx4 v[218:221], v143, s[2:3]
	global_load_dwordx4 v[230:233], v143, s[84:85] offset:256
	global_load_dwordx4 v[226:229], v143, s[2:3] offset:256
	s_waitcnt vmcnt(14)
	v_lshlrev_b32_e32 v234, 16, v150
	v_and_b32_e32 v235, 0xffff0000, v150
	v_lshlrev_b32_e32 v236, 16, v154
	v_and_b32_e32 v237, 0xffff0000, v154
	v_fmac_f32_e32 v236, v124, v234
	v_fmac_f32_e32 v237, v125, v235
	v_cvt_pk_bf16_f32 v150, v236, v237
	v_lshlrev_b32_e32 v244, 16, v151
	v_and_b32_e32 v245, 0xffff0000, v151
	v_lshlrev_b32_e32 v246, 16, v155
	v_and_b32_e32 v247, 0xffff0000, v155
	v_fmac_f32_e32 v246, v126, v244
	v_fmac_f32_e32 v247, v127, v245
	v_cvt_pk_bf16_f32 v151, v246, v247
	v_lshlrev_b32_e32 v248, 16, v152
	v_and_b32_e32 v249, 0xffff0000, v152
	v_lshlrev_b32_e32 v250, 16, v156
	v_and_b32_e32 v251, 0xffff0000, v156
	v_fmac_f32_e32 v250, v120, v248
	v_fmac_f32_e32 v251, v121, v249
	v_cvt_pk_bf16_f32 v152, v250, v251
	v_lshlrev_b32_e32 v188, 16, v153
	v_and_b32_e32 v189, 0xffff0000, v153
	v_lshlrev_b32_e32 v190, 16, v157
	v_and_b32_e32 v191, 0xffff0000, v157
	v_fmac_f32_e32 v190, v122, v188
	v_fmac_f32_e32 v191, v123, v189
	v_cvt_pk_bf16_f32 v153, v190, v191
	global_store_dwordx4 v140, v[150:153], s[84:85]
	global_load_dwordx4 v[154:157], v144, s[84:85]
	global_load_dwordx4 v[150:153], v144, s[2:3]
	s_waitcnt vmcnt(15)
	v_lshlrev_b32_e32 v234, 16, v158
	v_and_b32_e32 v235, 0xffff0000, v158
	v_lshlrev_b32_e32 v236, 16, v162
	v_and_b32_e32 v237, 0xffff0000, v162
	v_fmac_f32_e32 v236, v116, v234
	v_fmac_f32_e32 v237, v117, v235
	v_cvt_pk_bf16_f32 v158, v236, v237
	v_lshlrev_b32_e32 v244, 16, v159
	v_and_b32_e32 v245, 0xffff0000, v159
	v_lshlrev_b32_e32 v246, 16, v163
	v_and_b32_e32 v247, 0xffff0000, v163
	v_fmac_f32_e32 v246, v118, v244
	v_fmac_f32_e32 v247, v119, v245
	v_cvt_pk_bf16_f32 v159, v246, v247
	v_lshlrev_b32_e32 v248, 16, v160
	v_and_b32_e32 v249, 0xffff0000, v160
	v_lshlrev_b32_e32 v250, 16, v164
	v_and_b32_e32 v251, 0xffff0000, v164
	v_fmac_f32_e32 v250, v112, v248
	v_fmac_f32_e32 v251, v113, v249
	v_cvt_pk_bf16_f32 v160, v250, v251
	v_lshlrev_b32_e32 v188, 16, v161
	v_and_b32_e32 v189, 0xffff0000, v161
	v_lshlrev_b32_e32 v190, 16, v165
	v_and_b32_e32 v191, 0xffff0000, v165
	v_fmac_f32_e32 v190, v114, v188
	v_fmac_f32_e32 v191, v115, v189
	v_cvt_pk_bf16_f32 v161, v190, v191
	global_store_dwordx4 v140, v[158:161], s[84:85] offset:256
	global_load_dwordx4 v[162:165], v144, s[84:85] offset:256
	global_load_dwordx4 v[158:161], v144, s[2:3] offset:256
	s_waitcnt vmcnt(16)
	v_lshlrev_b32_e32 v234, 16, v166
	v_and_b32_e32 v235, 0xffff0000, v166
	v_lshlrev_b32_e32 v236, 16, v170
	v_and_b32_e32 v237, 0xffff0000, v170
	v_fmac_f32_e32 v236, v108, v234
	v_fmac_f32_e32 v237, v109, v235
	v_cvt_pk_bf16_f32 v166, v236, v237
	v_lshlrev_b32_e32 v244, 16, v167
	v_and_b32_e32 v245, 0xffff0000, v167
	v_lshlrev_b32_e32 v246, 16, v171
	v_and_b32_e32 v247, 0xffff0000, v171
	v_fmac_f32_e32 v246, v110, v244
	v_fmac_f32_e32 v247, v111, v245
	v_cvt_pk_bf16_f32 v167, v246, v247
	v_lshlrev_b32_e32 v248, 16, v168
	v_and_b32_e32 v249, 0xffff0000, v168
	v_lshlrev_b32_e32 v250, 16, v172
	v_and_b32_e32 v251, 0xffff0000, v172
	v_fmac_f32_e32 v250, v104, v248
	v_fmac_f32_e32 v251, v105, v249
	v_cvt_pk_bf16_f32 v168, v250, v251
	v_lshlrev_b32_e32 v188, 16, v169
	v_and_b32_e32 v189, 0xffff0000, v169
	v_lshlrev_b32_e32 v190, 16, v173
	v_and_b32_e32 v191, 0xffff0000, v173
	v_fmac_f32_e32 v190, v106, v188
	v_fmac_f32_e32 v191, v107, v189
	v_cvt_pk_bf16_f32 v169, v190, v191
	global_store_dwordx4 v141, v[166:169], s[84:85]
	global_load_dwordx4 v[170:173], v145, s[84:85]
	global_load_dwordx4 v[166:169], v145, s[2:3]
	s_waitcnt vmcnt(17)
	v_lshlrev_b32_e32 v234, 16, v174
	v_and_b32_e32 v235, 0xffff0000, v174
	v_lshlrev_b32_e32 v236, 16, v178
	v_and_b32_e32 v237, 0xffff0000, v178
	v_fmac_f32_e32 v236, v100, v234
	v_fmac_f32_e32 v237, v101, v235
	v_cvt_pk_bf16_f32 v174, v236, v237
	v_lshlrev_b32_e32 v244, 16, v175
	v_and_b32_e32 v245, 0xffff0000, v175
	v_lshlrev_b32_e32 v246, 16, v179
	v_and_b32_e32 v247, 0xffff0000, v179
	v_fmac_f32_e32 v246, v102, v244
	v_fmac_f32_e32 v247, v103, v245
	v_cvt_pk_bf16_f32 v175, v246, v247
	v_lshlrev_b32_e32 v248, 16, v176
	v_and_b32_e32 v249, 0xffff0000, v176
	v_lshlrev_b32_e32 v250, 16, v180
	v_and_b32_e32 v251, 0xffff0000, v180
	v_fmac_f32_e32 v250, v96, v248
	v_fmac_f32_e32 v251, v97, v249
	v_cvt_pk_bf16_f32 v176, v250, v251
	v_lshlrev_b32_e32 v188, 16, v177
	v_and_b32_e32 v189, 0xffff0000, v177
	v_lshlrev_b32_e32 v190, 16, v181
	v_and_b32_e32 v191, 0xffff0000, v181
	v_fmac_f32_e32 v190, v98, v188
	v_fmac_f32_e32 v191, v99, v189
	v_cvt_pk_bf16_f32 v177, v190, v191
	global_store_dwordx4 v141, v[174:177], s[84:85] offset:256
	global_load_dwordx4 v[178:181], v145, s[84:85] offset:256
	global_load_dwordx4 v[174:177], v145, s[2:3] offset:256
	s_waitcnt vmcnt(18)
; __device__ __forceinline__ float bf_lo(unsigned u) { return __uint_as_float(u << 16); }
; __device__ __forceinline__ float bf_hi(unsigned u) { return __uint_as_float(u & 0xffff0000u); }
; __device__ __forceinline__ u32x4 pk8(const f32x4& a, const f32x4& b) { u32x4 w; w.x = pk(a[0], a[1]); w.y = pk(a[2], a[3]); w.z = pk(b[0], b[1]); w.w = pk(b[2], b[3]); return w; }
;     __device__ __forceinline__ void operator()(const f32x4 (&acc)[2][2][4][2], const pg8::Unit& u, int wr, int wc, int fr, int fq) const { if (u.job) kv(acc, u, wr, wc, fr, fq); else q(acc, u, wr, wc, fr, fq); }
;     __device__ __forceinline__ void operator()(const f32x4 (&acc)[2][2][4][2], const pg8::Unit& u, int wr, int wc, int fr, int fq) const { if (u.job) e1(acc, u, wr, wc, fr, fq); else e0(acc, u, wr, wc, fr, fq); }
;     __device__ __forceinline__ void operator()(const f32x4 (&acc)[2][2][4][2], const pg8::Unit& u, int wr, int wc, int fr, int fq) const {
;         const int row0 = u.pm * 256 + wr * 64 + fr; const int col0 = u.pn * 256 + wc * 32 + 8 * fq;
; #pragma unroll
;         for (int ai = 0; ai < 2; ++ai)
; #pragma unroll
;             for (int m = 0; m < 4; ++m)
; #pragma unroll
;                 for (int bj = 0; bj < 2; ++bj) {
;                     const size_t off = (size_t)(row0 + ai * 128 + m * 16) * 2048 + col0 + bj * 128;
;                     const u32x4 g = *(const u32x4*)(G + off);
;                     f32x4 v0 = acc[ai][bj][m][0], v1 = acc[ai][bj][m][1];
;                     v0[0] *= bf_lo(g.x); v0[1] *= bf_hi(g.x); v0[2] *= bf_lo(g.y); v0[3] *= bf_hi(g.y);
;                     v1[0] *= bf_lo(g.z); v1[1] *= bf_hi(g.z); v1[2] *= bf_lo(g.w); v1[3] *= bf_hi(g.w);
;                     if (!first) { const u32x4 p = *(const u32x4*)(Mg + off);
;                         v0[0] += bf_lo(p.x); v0[1] += bf_hi(p.x); v0[2] += bf_lo(p.y); v0[3] += bf_hi(p.y);
;                         v1[0] += bf_lo(p.z); v1[1] += bf_hi(p.z); v1[2] += bf_lo(p.w); v1[3] += bf_hi(p.w); }
;                     *(u32x4*)(Mg + off) = pk8(v0, v1);
;                 }
	v_lshlrev_b32_e32 v234, 16, v202
	v_and_b32_e32 v235, 0xffff0000, v202
	v_lshlrev_b32_e32 v236, 16, v206
	v_and_b32_e32 v237, 0xffff0000, v206
	v_fmac_f32_e32 v236, v92, v234
	v_fmac_f32_e32 v237, v93, v235
	v_cvt_pk_bf16_f32 v202, v236, v237
	v_lshlrev_b32_e32 v244, 16, v203
	v_and_b32_e32 v245, 0xffff0000, v203
	v_lshlrev_b32_e32 v246, 16, v207
	v_and_b32_e32 v247, 0xffff0000, v207
	v_fmac_f32_e32 v246, v94, v244
	v_fmac_f32_e32 v247, v95, v245
	v_cvt_pk_bf16_f32 v203, v246, v247
	v_lshlrev_b32_e32 v248, 16, v204
	v_and_b32_e32 v249, 0xffff0000, v204
	v_lshlrev_b32_e32 v250, 16, v208
	v_and_b32_e32 v251, 0xffff0000, v208
	v_fmac_f32_e32 v250, v88, v248
	v_fmac_f32_e32 v251, v89, v249
	v_cvt_pk_bf16_f32 v204, v250, v251
	v_lshlrev_b32_e32 v188, 16, v205
	v_and_b32_e32 v189, 0xffff0000, v205
	v_lshlrev_b32_e32 v190, 16, v209
	v_and_b32_e32 v191, 0xffff0000, v209
	v_fmac_f32_e32 v190, v90, v188
	v_fmac_f32_e32 v191, v91, v189
	v_cvt_pk_bf16_f32 v205, v190, v191
	global_store_dwordx4 v142, v[202:205], s[84:85]
	global_load_dwordx4 v[206:209], v182, s[84:85]
	global_load_dwordx4 v[202:205], v182, s[2:3]
	s_waitcnt vmcnt(19)
	v_lshlrev_b32_e32 v234, 16, v210
	v_and_b32_e32 v235, 0xffff0000, v210
	v_lshlrev_b32_e32 v236, 16, v214
	v_and_b32_e32 v237, 0xffff0000, v214
	v_fmac_f32_e32 v236, v84, v234
	v_fmac_f32_e32 v237, v85, v235
	v_cvt_pk_bf16_f32 v210, v236, v237
	v_lshlrev_b32_e32 v244, 16, v211
	v_and_b32_e32 v245, 0xffff0000, v211
	v_lshlrev_b32_e32 v246, 16, v215
	v_and_b32_e32 v247, 0xffff0000, v215
	v_fmac_f32_e32 v246, v86, v244
	v_fmac_f32_e32 v247, v87, v245
	v_cvt_pk_bf16_f32 v211, v246, v247
	v_lshlrev_b32_e32 v248, 16, v212
	v_and_b32_e32 v249, 0xffff0000, v212
	v_lshlrev_b32_e32 v250, 16, v216
	v_and_b32_e32 v251, 0xffff0000, v216
	v_fmac_f32_e32 v250, v80, v248
	v_fmac_f32_e32 v251, v81, v249
	v_cvt_pk_bf16_f32 v212, v250, v251
	v_lshlrev_b32_e32 v188, 16, v213
	v_and_b32_e32 v189, 0xffff0000, v213
	v_lshlrev_b32_e32 v190, 16, v217
	v_and_b32_e32 v191, 0xffff0000, v217
	v_fmac_f32_e32 v190, v82, v188
	v_fmac_f32_e32 v191, v83, v189
	v_cvt_pk_bf16_f32 v213, v190, v191
	global_store_dwordx4 v142, v[210:213], s[84:85] offset:256
	global_load_dwordx4 v[214:217], v182, s[84:85] offset:256
	global_load_dwordx4 v[210:213], v182, s[2:3] offset:256
	s_waitcnt vmcnt(20)
	v_lshlrev_b32_e32 v234, 16, v218
	v_and_b32_e32 v235, 0xffff0000, v218
	v_lshlrev_b32_e32 v236, 16, v222
	v_and_b32_e32 v237, 0xffff0000, v222
	v_fmac_f32_e32 v236, v76, v234
	v_fmac_f32_e32 v237, v77, v235
	v_cvt_pk_bf16_f32 v218, v236, v237
	v_lshlrev_b32_e32 v244, 16, v219
	v_and_b32_e32 v245, 0xffff0000, v219
	v_lshlrev_b32_e32 v246, 16, v223
	v_and_b32_e32 v247, 0xffff0000, v223
	v_fmac_f32_e32 v246, v78, v244
	v_fmac_f32_e32 v247, v79, v245
	v_cvt_pk_bf16_f32 v219, v246, v247
	v_lshlrev_b32_e32 v248, 16, v220
	v_and_b32_e32 v249, 0xffff0000, v220
	v_lshlrev_b32_e32 v250, 16, v224
	v_and_b32_e32 v251, 0xffff0000, v224
	v_fmac_f32_e32 v250, v72, v248
	v_fmac_f32_e32 v251, v73, v249
	v_cvt_pk_bf16_f32 v220, v250, v251
	v_lshlrev_b32_e32 v188, 16, v221
	v_and_b32_e32 v189, 0xffff0000, v221
	v_lshlrev_b32_e32 v190, 16, v225
	v_and_b32_e32 v191, 0xffff0000, v225
	v_fmac_f32_e32 v190, v74, v188
	v_fmac_f32_e32 v191, v75, v189
	v_cvt_pk_bf16_f32 v221, v190, v191
	global_store_dwordx4 v143, v[218:221], s[84:85]
	global_load_dwordx4 v[222:225], v183, s[84:85]
	global_load_dwordx4 v[218:221], v183, s[2:3]
	s_waitcnt vmcnt(21)
	v_lshlrev_b32_e32 v234, 16, v226
	v_and_b32_e32 v235, 0xffff0000, v226
	v_lshlrev_b32_e32 v236, 16, v230
	v_and_b32_e32 v237, 0xffff0000, v230
	v_fmac_f32_e32 v236, v68, v234
	v_fmac_f32_e32 v237, v69, v235
	v_cvt_pk_bf16_f32 v226, v236, v237
	v_lshlrev_b32_e32 v244, 16, v227
	v_and_b32_e32 v245, 0xffff0000, v227
	v_lshlrev_b32_e32 v246, 16, v231
	v_and_b32_e32 v247, 0xffff0000, v231
	v_fmac_f32_e32 v246, v70, v244
	v_fmac_f32_e32 v247, v71, v245
	v_cvt_pk_bf16_f32 v227, v246, v247
	v_lshlrev_b32_e32 v248, 16, v228
	v_and_b32_e32 v249, 0xffff0000, v228
	v_lshlrev_b32_e32 v250, 16, v232
	v_and_b32_e32 v251, 0xffff0000, v232
	v_fmac_f32_e32 v250, v64, v248
	v_fmac_f32_e32 v251, v65, v249
	v_cvt_pk_bf16_f32 v228, v250, v251
	v_lshlrev_b32_e32 v188, 16, v229
	v_and_b32_e32 v189, 0xffff0000, v229
	v_lshlrev_b32_e32 v190, 16, v233
	v_and_b32_e32 v191, 0xffff0000, v233
	v_fmac_f32_e32 v190, v66, v188
	v_fmac_f32_e32 v191, v67, v189
	v_cvt_pk_bf16_f32 v229, v190, v191
	global_store_dwordx4 v143, v[226:229], s[84:85] offset:256
	global_load_dwordx4 v[230:233], v183, s[84:85] offset:256
	global_load_dwordx4 v[226:229], v183, s[2:3] offset:256
	s_waitcnt vmcnt(21)
	v_lshlrev_b32_e32 v234, 16, v150
	v_and_b32_e32 v235, 0xffff0000, v150
	v_lshlrev_b32_e32 v236, 16, v154
	v_and_b32_e32 v237, 0xffff0000, v154
	v_fmac_f32_e32 v236, v60, v234
	v_fmac_f32_e32 v237, v61, v235
	v_cvt_pk_bf16_f32 v150, v236, v237
	v_lshlrev_b32_e32 v244, 16, v151
	v_and_b32_e32 v245, 0xffff0000, v151
	v_lshlrev_b32_e32 v246, 16, v155
	v_and_b32_e32 v247, 0xffff0000, v155
	v_fmac_f32_e32 v246, v62, v244
	v_fmac_f32_e32 v247, v63, v245
	v_cvt_pk_bf16_f32 v151, v246, v247
	v_lshlrev_b32_e32 v248, 16, v152
	v_and_b32_e32 v249, 0xffff0000, v152
	v_lshlrev_b32_e32 v250, 16, v156
	v_and_b32_e32 v251, 0xffff0000, v156
	v_fmac_f32_e32 v250, v56, v248
	v_fmac_f32_e32 v251, v57, v249
	v_cvt_pk_bf16_f32 v152, v250, v251
	v_lshlrev_b32_e32 v188, 16, v153
	v_and_b32_e32 v189, 0xffff0000, v153
	v_lshlrev_b32_e32 v190, 16, v157
	v_and_b32_e32 v191, 0xffff0000, v157
	v_fmac_f32_e32 v190, v58, v188
	v_fmac_f32_e32 v191, v59, v189
	v_cvt_pk_bf16_f32 v153, v190, v191
	global_store_dwordx4 v144, v[150:153], s[84:85]
	s_waitcnt vmcnt(19)
; __device__ __forceinline__ float bf_lo(unsigned u) { return __uint_as_float(u << 16); }
; __device__ __forceinline__ float bf_hi(unsigned u) { return __uint_as_float(u & 0xffff0000u); }
; __device__ __forceinline__ u32x4 pk8(const f32x4& a, const f32x4& b) { u32x4 w; w.x = pk(a[0], a[1]); w.y = pk(a[2], a[3]); w.z = pk(b[0], b[1]); w.w = pk(b[2], b[3]); return w; }
;     __device__ __forceinline__ void operator()(const f32x4 (&acc)[2][2][4][2], const pg8::Unit& u, int wr, int wc, int fr, int fq) const { if (u.job) kv(acc, u, wr, wc, fr, fq); else q(acc, u, wr, wc, fr, fq); }
;     __device__ __forceinline__ void operator()(const f32x4 (&acc)[2][2][4][2], const pg8::Unit& u, int wr, int wc, int fr, int fq) const { if (u.job) e1(acc, u, wr, wc, fr, fq); else e0(acc, u, wr, wc, fr, fq); }
;     __device__ __forceinline__ void operator()(const f32x4 (&acc)[2][2][4][2], const pg8::Unit& u, int wr, int wc, int fr, int fq) const {
;         const int row0 = u.pm * 256 + wr * 64 + fr; const int col0 = u.pn * 256 + wc * 32 + 8 * fq;
; #pragma unroll
;         for (int ai = 0; ai < 2; ++ai)
; #pragma unroll
;             for (int m = 0; m < 4; ++m)
; #pragma unroll
;                 for (int bj = 0; bj < 2; ++bj) {
;                     const size_t off = (size_t)(row0 + ai * 128 + m * 16) * 2048 + col0 + bj * 128;
;                     const u32x4 g = *(const u32x4*)(G + off);
;                     f32x4 v0 = acc[ai][bj][m][0], v1 = acc[ai][bj][m][1];
;                     v0[0] *= bf_lo(g.x); v0[1] *= bf_hi(g.x); v0[2] *= bf_lo(g.y); v0[3] *= bf_hi(g.y);
;                     v1[0] *= bf_lo(g.z); v1[1] *= bf_hi(g.z); v1[2] *= bf_lo(g.w); v1[3] *= bf_hi(g.w);
;                     if (!first) { const u32x4 p = *(const u32x4*)(Mg + off);
;                         v0[0] += bf_lo(p.x); v0[1] += bf_hi(p.x); v0[2] += bf_lo(p.y); v0[3] += bf_hi(p.y);
;                         v1[0] += bf_lo(p.z); v1[1] += bf_hi(p.z); v1[2] += bf_lo(p.w); v1[3] += bf_hi(p.w); }
;                     *(u32x4*)(Mg + off) = pk8(v0, v1);
;                 }
	v_lshlrev_b32_e32 v234, 16, v158
	v_and_b32_e32 v235, 0xffff0000, v158
	v_lshlrev_b32_e32 v236, 16, v162
	v_and_b32_e32 v237, 0xffff0000, v162
	v_fmac_f32_e32 v236, v52, v234
	v_fmac_f32_e32 v237, v53, v235
	v_cvt_pk_bf16_f32 v158, v236, v237
	v_lshlrev_b32_e32 v244, 16, v159
	v_and_b32_e32 v245, 0xffff0000, v159
	v_lshlrev_b32_e32 v246, 16, v163
	v_and_b32_e32 v247, 0xffff0000, v163
	v_fmac_f32_e32 v246, v54, v244
	v_fmac_f32_e32 v247, v55, v245
	v_cvt_pk_bf16_f32 v159, v246, v247
	v_lshlrev_b32_e32 v248, 16, v160
	v_and_b32_e32 v249, 0xffff0000, v160
	v_lshlrev_b32_e32 v250, 16, v164
	v_and_b32_e32 v251, 0xffff0000, v164
	v_fmac_f32_e32 v250, v48, v248
	v_fmac_f32_e32 v251, v49, v249
	v_cvt_pk_bf16_f32 v160, v250, v251
	v_lshlrev_b32_e32 v188, 16, v161
	v_and_b32_e32 v189, 0xffff0000, v161
	v_lshlrev_b32_e32 v190, 16, v165
	v_and_b32_e32 v191, 0xffff0000, v165
	v_fmac_f32_e32 v190, v50, v188
	v_fmac_f32_e32 v191, v51, v189
	v_cvt_pk_bf16_f32 v161, v190, v191
	global_store_dwordx4 v144, v[158:161], s[84:85] offset:256
	s_waitcnt vmcnt(17)
	v_lshlrev_b32_e32 v234, 16, v166
	v_and_b32_e32 v235, 0xffff0000, v166
	v_lshlrev_b32_e32 v236, 16, v170
	v_and_b32_e32 v237, 0xffff0000, v170
	v_fmac_f32_e32 v236, v44, v234
	v_fmac_f32_e32 v237, v45, v235
	v_cvt_pk_bf16_f32 v166, v236, v237
	v_lshlrev_b32_e32 v244, 16, v167
	v_and_b32_e32 v245, 0xffff0000, v167
	v_lshlrev_b32_e32 v246, 16, v171
	v_and_b32_e32 v247, 0xffff0000, v171
	v_fmac_f32_e32 v246, v46, v244
	v_fmac_f32_e32 v247, v47, v245
	v_cvt_pk_bf16_f32 v167, v246, v247
	v_lshlrev_b32_e32 v248, 16, v168
	v_and_b32_e32 v249, 0xffff0000, v168
	v_lshlrev_b32_e32 v250, 16, v172
	v_and_b32_e32 v251, 0xffff0000, v172
	v_fmac_f32_e32 v250, v40, v248
	v_fmac_f32_e32 v251, v41, v249
	v_cvt_pk_bf16_f32 v168, v250, v251
	v_lshlrev_b32_e32 v188, 16, v169
	v_and_b32_e32 v189, 0xffff0000, v169
	v_lshlrev_b32_e32 v190, 16, v173
	v_and_b32_e32 v191, 0xffff0000, v173
	v_fmac_f32_e32 v190, v42, v188
	v_fmac_f32_e32 v191, v43, v189
	v_cvt_pk_bf16_f32 v169, v190, v191
	global_store_dwordx4 v145, v[166:169], s[84:85]
	s_waitcnt vmcnt(15)
	v_lshlrev_b32_e32 v234, 16, v174
	v_and_b32_e32 v235, 0xffff0000, v174
	v_lshlrev_b32_e32 v236, 16, v178
	v_and_b32_e32 v237, 0xffff0000, v178
	v_fmac_f32_e32 v236, v36, v234
	v_fmac_f32_e32 v237, v37, v235
	v_cvt_pk_bf16_f32 v174, v236, v237
	v_lshlrev_b32_e32 v244, 16, v175
	v_and_b32_e32 v245, 0xffff0000, v175
	v_lshlrev_b32_e32 v246, 16, v179
	v_and_b32_e32 v247, 0xffff0000, v179
	v_fmac_f32_e32 v246, v38, v244
	v_fmac_f32_e32 v247, v39, v245
	v_cvt_pk_bf16_f32 v175, v246, v247
	v_lshlrev_b32_e32 v248, 16, v176
	v_and_b32_e32 v249, 0xffff0000, v176
	v_lshlrev_b32_e32 v250, 16, v180
	v_and_b32_e32 v251, 0xffff0000, v180
	v_fmac_f32_e32 v250, v32, v248
	v_fmac_f32_e32 v251, v33, v249
	v_cvt_pk_bf16_f32 v176, v250, v251
	v_lshlrev_b32_e32 v188, 16, v177
	v_and_b32_e32 v189, 0xffff0000, v177
	v_lshlrev_b32_e32 v190, 16, v181
	v_and_b32_e32 v191, 0xffff0000, v181
	v_fmac_f32_e32 v190, v34, v188
	v_fmac_f32_e32 v191, v35, v189
	v_cvt_pk_bf16_f32 v177, v190, v191
	global_store_dwordx4 v145, v[174:177], s[84:85] offset:256
	s_waitcnt vmcnt(13)
	v_lshlrev_b32_e32 v234, 16, v202
	v_and_b32_e32 v235, 0xffff0000, v202
	v_lshlrev_b32_e32 v236, 16, v206
	v_and_b32_e32 v237, 0xffff0000, v206
	v_fmac_f32_e32 v236, v28, v234
	v_fmac_f32_e32 v237, v29, v235
	v_cvt_pk_bf16_f32 v202, v236, v237
	v_lshlrev_b32_e32 v244, 16, v203
	v_and_b32_e32 v245, 0xffff0000, v203
	v_lshlrev_b32_e32 v246, 16, v207
	v_and_b32_e32 v247, 0xffff0000, v207
	v_fmac_f32_e32 v246, v30, v244
	v_fmac_f32_e32 v247, v31, v245
	v_cvt_pk_bf16_f32 v203, v246, v247
	v_lshlrev_b32_e32 v248, 16, v204
	v_and_b32_e32 v249, 0xffff0000, v204
	v_lshlrev_b32_e32 v250, 16, v208
	v_and_b32_e32 v251, 0xffff0000, v208
	v_fmac_f32_e32 v250, v24, v248
	v_fmac_f32_e32 v251, v25, v249
	v_cvt_pk_bf16_f32 v204, v250, v251
	v_lshlrev_b32_e32 v188, 16, v205
	v_and_b32_e32 v189, 0xffff0000, v205
	v_lshlrev_b32_e32 v190, 16, v209
	v_and_b32_e32 v191, 0xffff0000, v209
	v_fmac_f32_e32 v190, v26, v188
	v_fmac_f32_e32 v191, v27, v189
	v_cvt_pk_bf16_f32 v205, v190, v191
	global_store_dwordx4 v182, v[202:205], s[84:85]
	s_waitcnt vmcnt(11)
; __device__ __forceinline__ float bf_lo(unsigned u) { return __uint_as_float(u << 16); }
; __device__ __forceinline__ float bf_hi(unsigned u) { return __uint_as_float(u & 0xffff0000u); }
; __device__ __forceinline__ u32x4 pk8(const f32x4& a, const f32x4& b) { u32x4 w; w.x = pk(a[0], a[1]); w.y = pk(a[2], a[3]); w.z = pk(b[0], b[1]); w.w = pk(b[2], b[3]); return w; }
;     __device__ __forceinline__ void operator()(const f32x4 (&acc)[2][2][4][2], const pg8::Unit& u, int wr, int wc, int fr, int fq) const { if (u.job) kv(acc, u, wr, wc, fr, fq); else q(acc, u, wr, wc, fr, fq); }
;     __device__ __forceinline__ void operator()(const f32x4 (&acc)[2][2][4][2], const pg8::Unit& u, int wr, int wc, int fr, int fq) const { if (u.job) e1(acc, u, wr, wc, fr, fq); else e0(acc, u, wr, wc, fr, fq); }
;     __device__ __forceinline__ void operator()(const f32x4 (&acc)[2][2][4][2], const pg8::Unit& u, int wr, int wc, int fr, int fq) const {
;         const int row0 = u.pm * 256 + wr * 64 + fr; const int col0 = u.pn * 256 + wc * 32 + 8 * fq;
; #pragma unroll
;         for (int ai = 0; ai < 2; ++ai)
; #pragma unroll
;             for (int m = 0; m < 4; ++m)
; #pragma unroll
;                 for (int bj = 0; bj < 2; ++bj) {
;                     const size_t off = (size_t)(row0 + ai * 128 + m * 16) * 2048 + col0 + bj * 128;
;                     const u32x4 g = *(const u32x4*)(G + off);
;                     f32x4 v0 = acc[ai][bj][m][0], v1 = acc[ai][bj][m][1];
;                     v0[0] *= bf_lo(g.x); v0[1] *= bf_hi(g.x); v0[2] *= bf_lo(g.y); v0[3] *= bf_hi(g.y);
;                     v1[0] *= bf_lo(g.z); v1[1] *= bf_hi(g.z); v1[2] *= bf_lo(g.w); v1[3] *= bf_hi(g.w);
;                     if (!first) { const u32x4 p = *(const u32x4*)(Mg + off);
;                         v0[0] += bf_lo(p.x); v0[1] += bf_hi(p.x); v0[2] += bf_lo(p.y); v0[3] += bf_hi(p.y);
;                         v1[0] += bf_lo(p.z); v1[1] += bf_hi(p.z); v1[2] += bf_lo(p.w); v1[3] += bf_hi(p.w); }
;                     *(u32x4*)(Mg + off) = pk8(v0, v1);
;                 }
	v_lshlrev_b32_e32 v234, 16, v210
	v_and_b32_e32 v235, 0xffff0000, v210
	v_lshlrev_b32_e32 v236, 16, v214
	v_and_b32_e32 v237, 0xffff0000, v214
	v_fmac_f32_e32 v236, v20, v234
	v_fmac_f32_e32 v237, v21, v235
	v_cvt_pk_bf16_f32 v210, v236, v237
	v_lshlrev_b32_e32 v244, 16, v211
	v_and_b32_e32 v245, 0xffff0000, v211
	v_lshlrev_b32_e32 v246, 16, v215
	v_and_b32_e32 v247, 0xffff0000, v215
	v_fmac_f32_e32 v246, v22, v244
	v_fmac_f32_e32 v247, v23, v245
	v_cvt_pk_bf16_f32 v211, v246, v247
	v_lshlrev_b32_e32 v248, 16, v212
	v_and_b32_e32 v249, 0xffff0000, v212
	v_lshlrev_b32_e32 v250, 16, v216
	v_and_b32_e32 v251, 0xffff0000, v216
	v_fmac_f32_e32 v250, v16, v248
	v_fmac_f32_e32 v251, v17, v249
	v_cvt_pk_bf16_f32 v212, v250, v251
	v_lshlrev_b32_e32 v188, 16, v213
	v_and_b32_e32 v189, 0xffff0000, v213
	v_lshlrev_b32_e32 v190, 16, v217
	v_and_b32_e32 v191, 0xffff0000, v217
	v_fmac_f32_e32 v190, v18, v188
	v_fmac_f32_e32 v191, v19, v189
	v_cvt_pk_bf16_f32 v213, v190, v191
	global_store_dwordx4 v182, v[210:213], s[84:85] offset:256
	s_waitcnt vmcnt(9)
	v_lshlrev_b32_e32 v234, 16, v218
	v_and_b32_e32 v235, 0xffff0000, v218
	v_lshlrev_b32_e32 v236, 16, v222
	v_and_b32_e32 v237, 0xffff0000, v222
	v_fmac_f32_e32 v236, v12, v234
	v_fmac_f32_e32 v237, v13, v235
	v_cvt_pk_bf16_f32 v218, v236, v237
	v_lshlrev_b32_e32 v244, 16, v219
	v_and_b32_e32 v245, 0xffff0000, v219
	v_lshlrev_b32_e32 v246, 16, v223
	v_and_b32_e32 v247, 0xffff0000, v223
	v_fmac_f32_e32 v246, v14, v244
	v_fmac_f32_e32 v247, v15, v245
	v_cvt_pk_bf16_f32 v219, v246, v247
	v_lshlrev_b32_e32 v248, 16, v220
	v_and_b32_e32 v249, 0xffff0000, v220
	v_lshlrev_b32_e32 v250, 16, v224
	v_and_b32_e32 v251, 0xffff0000, v224
	v_fmac_f32_e32 v250, v8, v248
	v_fmac_f32_e32 v251, v9, v249
	v_cvt_pk_bf16_f32 v220, v250, v251
	v_lshlrev_b32_e32 v188, 16, v221
	v_and_b32_e32 v189, 0xffff0000, v221
	v_lshlrev_b32_e32 v190, 16, v225
	v_and_b32_e32 v191, 0xffff0000, v225
	v_fmac_f32_e32 v190, v10, v188
	v_fmac_f32_e32 v191, v11, v189
	v_cvt_pk_bf16_f32 v221, v190, v191
	global_store_dwordx4 v183, v[218:221], s[84:85]
	s_waitcnt vmcnt(7)
	v_lshlrev_b32_e32 v234, 16, v226
	v_and_b32_e32 v235, 0xffff0000, v226
	v_lshlrev_b32_e32 v236, 16, v230
	v_and_b32_e32 v237, 0xffff0000, v230
	v_fmac_f32_e32 v236, v4, v234
	v_fmac_f32_e32 v237, v5, v235
	v_cvt_pk_bf16_f32 v226, v236, v237
	v_lshlrev_b32_e32 v244, 16, v227
	v_and_b32_e32 v245, 0xffff0000, v227
	v_lshlrev_b32_e32 v246, 16, v231
	v_and_b32_e32 v247, 0xffff0000, v231
	v_fmac_f32_e32 v246, v6, v244
	v_fmac_f32_e32 v247, v7, v245
	v_cvt_pk_bf16_f32 v227, v246, v247
	v_lshlrev_b32_e32 v248, 16, v228
	v_and_b32_e32 v249, 0xffff0000, v228
	v_lshlrev_b32_e32 v250, 16, v232
	v_and_b32_e32 v251, 0xffff0000, v232
	v_fmac_f32_e32 v250, v0, v248
	v_fmac_f32_e32 v251, v1, v249
	v_cvt_pk_bf16_f32 v228, v250, v251
	v_lshlrev_b32_e32 v188, 16, v229
	v_and_b32_e32 v189, 0xffff0000, v229
	v_lshlrev_b32_e32 v190, 16, v233
	v_and_b32_e32 v191, 0xffff0000, v233
	v_fmac_f32_e32 v190, v2, v188
	v_fmac_f32_e32 v191, v3, v189
	v_cvt_pk_bf16_f32 v229, v190, v191
	global_store_dwordx4 v183, v[226:229], s[84:85] offset:256
	s_mov_b64 s[34:35], -1
	s_cbranch_vccnz .LBB0_1164
	s_andn2_b64 vcc, exec, s[8:9]
	s_cbranch_vccnz .LBB0_1163
	s_barrier
	s_branch .LBB0_1163

;     __device__ __forceinline__ void operator()(const f32x4 (&acc)[2][2][4][2], const pg8::Unit& u, int wr, int wc, int fr, int fq) const { if (u.job) kv(acc, u, wr, wc, fr, fq); else q(acc, u, wr, wc, fr, fq); }
;     __device__ __forceinline__ void operator()(const f32x4 (&acc)[2][2][4][2], const pg8::Unit& u, int wr, int wc, int fr, int fq) const { if (u.job) e1(acc, u, wr, wc, fr, fq); else e0(acc, u, wr, wc, fr, fq); }
;     __device__ __forceinline__ void operator()(const f32x4 (&acc)[2][2][4][2], const pg8::Unit& u, int wr, int wc, int fr, int fq) const {
;         const int row0 = u.pm * 256 + wr * 64 + fr; const int col0 = u.pn * 256 + wc * 32 + 8 * fq;
; #pragma unroll
;         for (int ai = 0; ai < 2; ++ai)
; #pragma unroll
;             for (int m = 0; m < 4; ++m)
; #pragma unroll
;                 for (int bj = 0; bj < 2; ++bj) {
;                     const size_t off = (size_t)(row0 + ai * 128 + m * 16) * 2048 + col0 + bj * 128;
;                     const f32x4 x0 = *(const f32x4*)(X + off), x1 = *(const f32x4*)(X + off + 4);
;                     *(f32x4*)(O + off) = x0 + acc[ai][bj][m][0]; *(f32x4*)(O + off + 4) = x1 + acc[ai][bj][m][1];
;                 }
.LBB0_1247:
	v_lshl_add_u32 v193, s48, 8, v146
	v_lshl_or_b32 v140, s44, 8, v148
	v_lshlrev_b32_e32 v140, 2, v140
	v_lshl_add_u32 v140, v193, 13, v140
	v_add_u32_e32 v141, 0x20000, v140
	v_add_u32_e32 v142, 0x40000, v140
	v_add_u32_e32 v143, 0x60000, v140
	v_add_u32_e32 v144, 0x100000, v140
	v_add_u32_e32 v145, 0x120000, v140
	v_add_u32_e32 v182, 0x140000, v140
	v_add_u32_e32 v183, 0x160000, v140
	s_nop 15
	s_nop 3
	s_andn2_b64 vcc, exec, s[4:5]
	global_load_dwordx4 v[150:153], v140, s[8:9]
	global_load_dwordx4 v[154:157], v140, s[8:9] offset:16
	global_load_dwordx4 v[158:161], v140, s[8:9] offset:512
	global_load_dwordx4 v[162:165], v140, s[8:9] offset:528
	global_load_dwordx4 v[166:169], v141, s[8:9]
	global_load_dwordx4 v[170:173], v141, s[8:9] offset:16
	global_load_dwordx4 v[174:177], v141, s[8:9] offset:512
	global_load_dwordx4 v[178:181], v141, s[8:9] offset:528
	global_load_dwordx4 v[202:205], v142, s[8:9]
	global_load_dwordx4 v[206:209], v142, s[8:9] offset:16
	global_load_dwordx4 v[210:213], v142, s[8:9] offset:512
	global_load_dwordx4 v[214:217], v142, s[8:9] offset:528
	global_load_dwordx4 v[218:221], v143, s[8:9]
	global_load_dwordx4 v[222:225], v143, s[8:9] offset:16
	global_load_dwordx4 v[226:229], v143, s[8:9] offset:512
	global_load_dwordx4 v[230:233], v143, s[8:9] offset:528
	s_waitcnt vmcnt(14)
	v_pk_add_f32 v[124:125], v[124:125], v[150:151]
	v_pk_add_f32 v[126:127], v[126:127], v[152:153]
	v_pk_add_f32 v[120:121], v[120:121], v[154:155]
	v_pk_add_f32 v[122:123], v[122:123], v[156:157]
	global_store_dwordx4 v140, v[124:127], s[12:13]
	global_store_dwordx4 v140, v[120:123], s[12:13] offset:16
	global_load_dwordx4 v[150:153], v144, s[8:9]
	global_load_dwordx4 v[154:157], v144, s[8:9] offset:16
	s_waitcnt vmcnt(16)
	v_pk_add_f32 v[116:117], v[116:117], v[158:159]
	v_pk_add_f32 v[118:119], v[118:119], v[160:161]
	v_pk_add_f32 v[112:113], v[112:113], v[162:163]
	v_pk_add_f32 v[114:115], v[114:115], v[164:165]
	global_store_dwordx4 v140, v[116:119], s[12:13] offset:512
	global_store_dwordx4 v140, v[112:115], s[12:13] offset:528
	global_load_dwordx4 v[158:161], v144, s[8:9] offset:512
	global_load_dwordx4 v[162:165], v144, s[8:9] offset:528
	s_waitcnt vmcnt(18)
	v_pk_add_f32 v[108:109], v[108:109], v[166:167]
	v_pk_add_f32 v[110:111], v[110:111], v[168:169]
	v_pk_add_f32 v[104:105], v[104:105], v[170:171]
	v_pk_add_f32 v[106:107], v[106:107], v[172:173]
	global_store_dwordx4 v141, v[108:111], s[12:13]
	global_store_dwordx4 v141, v[104:107], s[12:13] offset:16
	global_load_dwordx4 v[166:169], v145, s[8:9]
	global_load_dwordx4 v[170:173], v145, s[8:9] offset:16
	s_waitcnt vmcnt(20)
	v_pk_add_f32 v[100:101], v[100:101], v[174:175]
	v_pk_add_f32 v[102:103], v[102:103], v[176:177]
	v_pk_add_f32 v[96:97], v[96:97], v[178:179]
	v_pk_add_f32 v[98:99], v[98:99], v[180:181]
	global_store_dwordx4 v141, v[100:103], s[12:13] offset:512
	global_store_dwordx4 v141, v[96:99], s[12:13] offset:528
	global_load_dwordx4 v[174:177], v145, s[8:9] offset:512
	global_load_dwordx4 v[178:181], v145, s[8:9] offset:528
	s_waitcnt vmcnt(22)
	v_pk_add_f32 v[92:93], v[92:93], v[202:203]
	v_pk_add_f32 v[94:95], v[94:95], v[204:205]
	v_pk_add_f32 v[88:89], v[88:89], v[206:207]
	v_pk_add_f32 v[90:91], v[90:91], v[208:209]
	global_store_dwordx4 v142, v[92:95], s[12:13]
	global_store_dwordx4 v142, v[88:91], s[12:13] offset:16
	global_load_dwordx4 v[202:205], v182, s[8:9]
	global_load_dwordx4 v[206:209], v182, s[8:9] offset:16
	s_waitcnt vmcnt(24)
;     __device__ __forceinline__ void operator()(const f32x4 (&acc)[2][2][4][2], const pg8::Unit& u, int wr, int wc, int fr, int fq) const { if (u.job) kv(acc, u, wr, wc, fr, fq); else q(acc, u, wr, wc, fr, fq); }
;     __device__ __forceinline__ void operator()(const f32x4 (&acc)[2][2][4][2], const pg8::Unit& u, int wr, int wc, int fr, int fq) const { if (u.job) e1(acc, u, wr, wc, fr, fq); else e0(acc, u, wr, wc, fr, fq); }
;     __device__ __forceinline__ void operator()(const f32x4 (&acc)[2][2][4][2], const pg8::Unit& u, int wr, int wc, int fr, int fq) const {
;         const int row0 = u.pm * 256 + wr * 64 + fr; const int col0 = u.pn * 256 + wc * 32 + 8 * fq;
; #pragma unroll
;         for (int ai = 0; ai < 2; ++ai)
; #pragma unroll
;             for (int m = 0; m < 4; ++m)
; #pragma unroll
;                 for (int bj = 0; bj < 2; ++bj) {
;                     const size_t off = (size_t)(row0 + ai * 128 + m * 16) * 2048 + col0 + bj * 128;
;                     const f32x4 x0 = *(const f32x4*)(X + off), x1 = *(const f32x4*)(X + off + 4);
;                     *(f32x4*)(O + off) = x0 + acc[ai][bj][m][0]; *(f32x4*)(O + off + 4) = x1 + acc[ai][bj][m][1];
;                 }
	v_pk_add_f32 v[84:85], v[84:85], v[210:211]
	v_pk_add_f32 v[86:87], v[86:87], v[212:213]
	v_pk_add_f32 v[80:81], v[80:81], v[214:215]
	v_pk_add_f32 v[82:83], v[82:83], v[216:217]
	global_store_dwordx4 v142, v[84:87], s[12:13] offset:512
	global_store_dwordx4 v142, v[80:83], s[12:13] offset:528
	global_load_dwordx4 v[210:213], v182, s[8:9] offset:512
	global_load_dwordx4 v[214:217], v182, s[8:9] offset:528
	s_waitcnt vmcnt(26)
	v_pk_add_f32 v[76:77], v[76:77], v[218:219]
	v_pk_add_f32 v[78:79], v[78:79], v[220:221]
	v_pk_add_f32 v[72:73], v[72:73], v[222:223]
	v_pk_add_f32 v[74:75], v[74:75], v[224:225]
	global_store_dwordx4 v143, v[76:79], s[12:13]
	global_store_dwordx4 v143, v[72:75], s[12:13] offset:16
	global_load_dwordx4 v[218:221], v183, s[8:9]
	global_load_dwordx4 v[222:225], v183, s[8:9] offset:16
	s_waitcnt vmcnt(28)
	v_pk_add_f32 v[68:69], v[68:69], v[226:227]
	v_pk_add_f32 v[70:71], v[70:71], v[228:229]
	v_pk_add_f32 v[64:65], v[64:65], v[230:231]
	v_pk_add_f32 v[66:67], v[66:67], v[232:233]
	global_store_dwordx4 v143, v[68:71], s[12:13] offset:512
	global_store_dwordx4 v143, v[64:67], s[12:13] offset:528
	global_load_dwordx4 v[226:229], v183, s[8:9] offset:512
	global_load_dwordx4 v[230:233], v183, s[8:9] offset:528
	s_waitcnt vmcnt(28)
	v_pk_add_f32 v[60:61], v[60:61], v[150:151]
	v_pk_add_f32 v[62:63], v[62:63], v[152:153]
	v_pk_add_f32 v[56:57], v[56:57], v[154:155]
	v_pk_add_f32 v[58:59], v[58:59], v[156:157]
	global_store_dwordx4 v144, v[60:63], s[12:13]
	global_store_dwordx4 v144, v[56:59], s[12:13] offset:16
	s_waitcnt vmcnt(26)
	v_pk_add_f32 v[52:53], v[52:53], v[158:159]
	v_pk_add_f32 v[54:55], v[54:55], v[160:161]
	v_pk_add_f32 v[48:49], v[48:49], v[162:163]
	v_pk_add_f32 v[50:51], v[50:51], v[164:165]
	global_store_dwordx4 v144, v[52:55], s[12:13] offset:512
	global_store_dwordx4 v144, v[48:51], s[12:13] offset:528
	s_waitcnt vmcnt(24)
	v_pk_add_f32 v[44:45], v[44:45], v[166:167]
	v_pk_add_f32 v[46:47], v[46:47], v[168:169]
	v_pk_add_f32 v[40:41], v[40:41], v[170:171]
	v_pk_add_f32 v[42:43], v[42:43], v[172:173]
	global_store_dwordx4 v145, v[44:47], s[12:13]
	global_store_dwordx4 v145, v[40:43], s[12:13] offset:16
	s_waitcnt vmcnt(22)
	v_pk_add_f32 v[36:37], v[36:37], v[174:175]
	v_pk_add_f32 v[38:39], v[38:39], v[176:177]
	v_pk_add_f32 v[32:33], v[32:33], v[178:179]
	v_pk_add_f32 v[34:35], v[34:35], v[180:181]
	global_store_dwordx4 v145, v[36:39], s[12:13] offset:512
	global_store_dwordx4 v145, v[32:35], s[12:13] offset:528
	s_waitcnt vmcnt(20)
	v_pk_add_f32 v[28:29], v[28:29], v[202:203]
	v_pk_add_f32 v[30:31], v[30:31], v[204:205]
	v_pk_add_f32 v[24:25], v[24:25], v[206:207]
	v_pk_add_f32 v[26:27], v[26:27], v[208:209]
	global_store_dwordx4 v182, v[28:31], s[12:13]
	global_store_dwordx4 v182, v[24:27], s[12:13] offset:16
	s_waitcnt vmcnt(18)
	v_pk_add_f32 v[20:21], v[20:21], v[210:211]
	v_pk_add_f32 v[22:23], v[22:23], v[212:213]
	v_pk_add_f32 v[16:17], v[16:17], v[214:215]
	v_pk_add_f32 v[18:19], v[18:19], v[216:217]
	global_store_dwordx4 v182, v[20:23], s[12:13] offset:512
	global_store_dwordx4 v182, v[16:19], s[12:13] offset:528
	s_waitcnt vmcnt(16)
	v_pk_add_f32 v[12:13], v[12:13], v[218:219]
	v_pk_add_f32 v[14:15], v[14:15], v[220:221]
	v_pk_add_f32 v[8:9], v[8:9], v[222:223]
	v_pk_add_f32 v[10:11], v[10:11], v[224:225]
	global_store_dwordx4 v183, v[12:15], s[12:13]
	global_store_dwordx4 v183, v[8:11], s[12:13] offset:16
	s_waitcnt vmcnt(14)
	v_pk_add_f32 v[4:5], v[4:5], v[226:227]
	v_pk_add_f32 v[6:7], v[6:7], v[228:229]
	v_pk_add_f32 v[0:1], v[0:1], v[230:231]
	v_pk_add_f32 v[2:3], v[2:3], v[232:233]
	global_store_dwordx4 v183, v[4:7], s[12:13] offset:512
	global_store_dwordx4 v183, v[0:3], s[12:13] offset:528
	s_mov_b64 s[34:35], -1
	s_cbranch_vccnz .LBB0_1236
	s_andn2_b64 vcc, exec, s[6:7]
	s_cbranch_vccnz .LBB0_1235
	s_barrier
	s_branch .LBB0_1235
